# nt hint on the out-projection epilogue residual-row loads (layers 1-3)
# speedup vs baseline: 1.0066x; 1.0066x over previous
.Lfo_entry:
	s_and_b64 vcc, exec, s[28:29]
	s_cbranch_vccz .Lfo_first
	s_lshr_b32 s14, s34, 3
	s_mul_i32 s14, s14, 0x3000
	s_add_u32 s16, s86, s14
	s_addc_u32 s17, s87, 0
	s_add_u32 s16, s16, 0x2000
	s_addc_u32 s17, s17, 0
	s_add_u32 s86, s88, s14
	s_addc_u32 s87, s89, 0
	s_add_u32 s86, s86, 0x1000
	s_addc_u32 s87, s87, 0
	v_lshl_add_u32 v171, v170, 1, v96
	v_lshl_add_u32 v171, v222, 11, v171
	v_lshlrev_b32_e32 v170, 2, v170
	s_lshl_b32 s14, s34, 8
	s_add_i32 s14, s14, s81
	s_lshl_b32 s12, s14, 11
	s_add_u32 s14, s2, s12
	s_addc_u32 s15, s3, 0
	s_add_u32 s78, s78, s12
	s_addc_u32 s79, s79, 0
	s_add_u32 s22, s78, 0x4000
	s_addc_u32 s23, s79, 0
	s_mov_b64 s[2:3], s[14:15]
	s_add_u32 s18, s14, 0x4000
	s_addc_u32 s19, s15, 0
	s_mov_b64 s[12:13], s[18:19]
	s_and_b64 vcc, exec, s[40:41]
	s_cbranch_vccz .Lfo_nong
	global_load_dwordx4 v[142:145], v170, s[16:17]
	global_load_dwordx4 v[150:153], v170, s[16:17] offset:16
	global_load_dwordx4 v[138:141], v170, s[16:17] offset:128
	global_load_dwordx4 v[146:149], v170, s[16:17] offset:144
	global_load_dwordx4 v[196:199], v171, s[14:15] nt
	global_load_dwordx4 v[200:203], v171, s[12:13] nt
	s_add_u32 s14, s14, 0x8000
	s_addc_u32 s15, s15, 0
	s_add_u32 s12, s12, 0x8000
	s_addc_u32 s13, s13, 0
	global_load_dwordx4 v[204:207], v171, s[14:15] nt
	global_load_dwordx4 v[234:237], v171, s[12:13] nt
	global_load_dwordx4 v[180:183], v170, s[86:87]
	global_load_dwordx4 v[184:187], v170, s[86:87] offset:16
	global_load_dwordx4 v[188:191], v170, s[86:87] offset:128
	global_load_dwordx4 v[192:195], v170, s[86:87] offset:144
	global_load_dwordx4 v[0:3], v170, s[26:27]
	global_load_dwordx4 v[4:7], v170, s[26:27] offset:16
	global_load_dwordx4 v[238:241], v170, s[26:27] offset:128
	global_load_dwordx4 v[242:245], v170, s[26:27] offset:144
	s_waitcnt vmcnt(0)
	v_pk_add_f32 v[182:183], v[182:183], 1.0 op_sel_hi:[1,0]
	v_pk_add_f32 v[180:181], v[180:181], 1.0 op_sel_hi:[1,0]
	v_pk_add_f32 v[186:187], v[186:187], 1.0 op_sel_hi:[1,0]
	v_pk_add_f32 v[184:185], v[184:185], 1.0 op_sel_hi:[1,0]
	v_pk_add_f32 v[190:191], v[190:191], 1.0 op_sel_hi:[1,0]
	v_pk_add_f32 v[188:189], v[188:189], 1.0 op_sel_hi:[1,0]
	v_pk_add_f32 v[194:195], v[194:195], 1.0 op_sel_hi:[1,0]
	v_pk_add_f32 v[192:193], v[192:193], 1.0 op_sel_hi:[1,0]
	v_pk_mul_f32 v[182:183], v[2:3], v[182:183]
	v_pk_mul_f32 v[180:181], v[0:1], v[180:181]
	v_pk_mul_f32 v[186:187], v[6:7], v[186:187]
	v_pk_mul_f32 v[184:185], v[4:5], v[184:185]
	v_pk_mul_f32 v[190:191], v[240:241], v[190:191]
	v_pk_mul_f32 v[188:189], v[238:239], v[188:189]
	v_pk_mul_f32 v[194:195], v[244:245], v[194:195]
	v_pk_mul_f32 v[192:193], v[242:243], v[192:193]
	s_add_u32 s14, s14, 0x8000
	s_addc_u32 s15, s15, 0
	s_add_u32 s12, s12, 0x8000
	s_addc_u32 s13, s13, 0
	global_load_dwordx4 v[238:241], v171, s[14:15] nt
	global_load_dwordx4 v[242:245], v171, s[12:13] nt
	s_waitcnt vmcnt(2)
	s_mov_b64 vcc, s[6:7]
	v_cndmask_b32_dpp v0, v200, v196, vcc row_ror:8 row_mask:0xf bank_mask:0xf
	v_cndmask_b32_dpp v1, v201, v197, vcc row_ror:8 row_mask:0xf bank_mask:0xf
	v_cndmask_b32_dpp v2, v202, v198, vcc row_ror:8 row_mask:0xf bank_mask:0xf
	v_cndmask_b32_dpp v3, v203, v199, vcc row_ror:8 row_mask:0xf bank_mask:0xf
	s_not_b64 vcc, s[6:7]
	v_cndmask_b32_dpp v4, v196, v200, vcc row_ror:8 row_mask:0xf bank_mask:0xf
	v_cndmask_b32_dpp v5, v197, v201, vcc row_ror:8 row_mask:0xf bank_mask:0xf
	v_cndmask_b32_dpp v6, v198, v202, vcc row_ror:8 row_mask:0xf bank_mask:0xf
	v_cndmask_b32_dpp v7, v199, v203, vcc row_ror:8 row_mask:0xf bank_mask:0xf
	s_add_u32 s14, s14, 0x8000
	s_addc_u32 s15, s15, 0
	s_add_u32 s12, s12, 0x8000
	s_addc_u32 s13, s13, 0
	global_load_dwordx4 v[196:199], v171, s[14:15] nt
	global_load_dwordx4 v[200:203], v171, s[12:13] nt
	v_lshlrev_b32_e32 v246, 16, v0
	v_and_b32_e32 v247, 0xffff0000, v0
	v_pk_fma_f32 v[134:135], v[134:135], v[142:143], v[246:247]
	v_lshlrev_b32_e32 v248, 16, v1
	v_and_b32_e32 v249, 0xffff0000, v1
	v_pk_fma_f32 v[136:137], v[136:137], v[144:145], v[248:249]
	v_lshlrev_b32_e32 v250, 16, v2
	v_and_b32_e32 v251, 0xffff0000, v2
	v_pk_fma_f32 v[130:131], v[130:131], v[150:151], v[250:251]
	v_lshlrev_b32_e32 v208, 16, v3
	v_and_b32_e32 v209, 0xffff0000, v3
	v_pk_fma_f32 v[132:133], v[132:133], v[152:153], v[208:209]
	v_lshlrev_b32_e32 v246, 16, v4
	v_and_b32_e32 v247, 0xffff0000, v4
	v_pk_fma_f32 v[126:127], v[126:127], v[138:139], v[246:247]
	v_lshlrev_b32_e32 v248, 16, v5
	v_and_b32_e32 v249, 0xffff0000, v5
	v_pk_fma_f32 v[128:129], v[128:129], v[140:141], v[248:249]
	v_lshlrev_b32_e32 v250, 16, v6
	v_and_b32_e32 v251, 0xffff0000, v6
	v_pk_fma_f32 v[122:123], v[122:123], v[146:147], v[250:251]
	v_lshlrev_b32_e32 v208, 16, v7
	v_and_b32_e32 v209, 0xffff0000, v7
	v_pk_fma_f32 v[124:125], v[124:125], v[148:149], v[208:209]
	v_cvt_pk_bf16_f32 v0, v134, v135
	v_cvt_pk_bf16_f32 v1, v136, v137
	v_cvt_pk_bf16_f32 v2, v130, v131
	v_cvt_pk_bf16_f32 v3, v132, v133
	v_cvt_pk_bf16_f32 v4, v126, v127
	v_cvt_pk_bf16_f32 v5, v128, v129
	v_cvt_pk_bf16_f32 v6, v122, v123
	v_cvt_pk_bf16_f32 v7, v124, v125
	v_mul_f32_e32 v246, v135, v135
	v_mul_f32_e32 v248, v137, v137
	v_fmac_f32_e32 v246, v134, v134
	v_fmac_f32_e32 v248, v136, v136
	v_add_f32_e32 v246, v246, v248
	v_mul_f32_e32 v248, v131, v131
	v_fmac_f32_e32 v248, v130, v130
	v_add_f32_e32 v246, v246, v248
	v_mul_f32_e32 v248, v133, v133
	v_fmac_f32_e32 v248, v132, v132
	v_add_f32_e32 v246, v248, v246
	v_mul_f32_e32 v247, v127, v127
	v_mul_f32_e32 v248, v129, v129
	v_fmac_f32_e32 v247, v126, v126
	v_fmac_f32_e32 v248, v128, v128
	v_add_f32_e32 v247, v247, v248
	v_mul_f32_e32 v248, v123, v123
	v_fmac_f32_e32 v248, v122, v122
	v_add_f32_e32 v247, v247, v248
	v_mul_f32_e32 v248, v125, v125
	v_fmac_f32_e32 v248, v124, v124
	v_add_f32_e32 v247, v248, v247
	v_add_f32_e32 v246, v246, v247
	v_mov_b32_e32 v247, v246
	s_nop 1
	v_permlane16_swap_b32_e32 v246, v247
	s_nop 1
	v_add_f32_e32 v246, v246, v247
	v_mov_b32_e32 v247, v246
	s_nop 1
	v_permlane32_swap_b32_e32 v246, v247
	v_add_u32_e32 v248, s8, v223
	s_nop 0
	v_add_f32_e32 v246, v246, v247
	s_mov_b64 exec, s[44:45]
	ds_write_b32 v248, v246
	s_mov_b64 exec, -1
	v_pk_mul_f32 v[134:135], v[180:181], v[134:135]
	v_pk_mul_f32 v[136:137], v[182:183], v[136:137]
	v_pk_mul_f32 v[130:131], v[184:185], v[130:131]
	v_pk_mul_f32 v[132:133], v[186:187], v[132:133]
	v_pk_mul_f32 v[126:127], v[188:189], v[126:127]
	v_pk_mul_f32 v[128:129], v[190:191], v[128:129]
	v_pk_mul_f32 v[122:123], v[192:193], v[122:123]
	v_pk_mul_f32 v[124:125], v[194:195], v[124:125]
	v_cvt_pk_bf16_f32 v246, v134, v135
	v_cvt_pk_bf16_f32 v247, v136, v137
	v_cvt_pk_bf16_f32 v248, v130, v131
	v_cvt_pk_bf16_f32 v249, v132, v133
	v_cvt_pk_bf16_f32 v250, v126, v127
	v_cvt_pk_bf16_f32 v251, v128, v129
	v_cvt_pk_bf16_f32 v208, v122, v123
	v_cvt_pk_bf16_f32 v209, v124, v125
	s_nop 1
	s_mov_b64 vcc, s[6:7]
	v_cndmask_b32_dpp v134, v4, v0, vcc row_ror:8 row_mask:0xf bank_mask:0xf
	v_cndmask_b32_dpp v135, v5, v1, vcc row_ror:8 row_mask:0xf bank_mask:0xf
	v_cndmask_b32_dpp v136, v6, v2, vcc row_ror:8 row_mask:0xf bank_mask:0xf
	v_cndmask_b32_dpp v137, v7, v3, vcc row_ror:8 row_mask:0xf bank_mask:0xf
	v_cndmask_b32_dpp v126, v250, v246, vcc row_ror:8 row_mask:0xf bank_mask:0xf
	v_cndmask_b32_dpp v127, v251, v247, vcc row_ror:8 row_mask:0xf bank_mask:0xf
	v_cndmask_b32_dpp v128, v208, v248, vcc row_ror:8 row_mask:0xf bank_mask:0xf
	v_cndmask_b32_dpp v129, v209, v249, vcc row_ror:8 row_mask:0xf bank_mask:0xf
	s_not_b64 vcc, s[6:7]
	v_cndmask_b32_dpp v130, v0, v4, vcc row_ror:8 row_mask:0xf bank_mask:0xf
	v_cndmask_b32_dpp v131, v1, v5, vcc row_ror:8 row_mask:0xf bank_mask:0xf
	v_cndmask_b32_dpp v132, v2, v6, vcc row_ror:8 row_mask:0xf bank_mask:0xf
	v_cndmask_b32_dpp v133, v3, v7, vcc row_ror:8 row_mask:0xf bank_mask:0xf
	v_cndmask_b32_dpp v122, v246, v250, vcc row_ror:8 row_mask:0xf bank_mask:0xf
	v_cndmask_b32_dpp v123, v247, v251, vcc row_ror:8 row_mask:0xf bank_mask:0xf
	v_cndmask_b32_dpp v124, v248, v208, vcc row_ror:8 row_mask:0xf bank_mask:0xf
	v_cndmask_b32_dpp v125, v249, v209, vcc row_ror:8 row_mask:0xf bank_mask:0xf
	global_store_dwordx4 v171, v[134:137], s[2:3]
	global_store_dwordx4 v171, v[130:133], s[18:19]
	global_store_dwordx4 v171, v[126:129], s[78:79]
	global_store_dwordx4 v171, v[122:125], s[22:23]
	s_waitcnt vmcnt(8)
	s_mov_b64 vcc, s[6:7]
	v_cndmask_b32_dpp v0, v234, v204, vcc row_ror:8 row_mask:0xf bank_mask:0xf
	v_cndmask_b32_dpp v1, v235, v205, vcc row_ror:8 row_mask:0xf bank_mask:0xf
	v_cndmask_b32_dpp v2, v236, v206, vcc row_ror:8 row_mask:0xf bank_mask:0xf
	v_cndmask_b32_dpp v3, v237, v207, vcc row_ror:8 row_mask:0xf bank_mask:0xf
	s_not_b64 vcc, s[6:7]
	v_cndmask_b32_dpp v4, v204, v234, vcc row_ror:8 row_mask:0xf bank_mask:0xf
	v_cndmask_b32_dpp v5, v205, v235, vcc row_ror:8 row_mask:0xf bank_mask:0xf
	v_cndmask_b32_dpp v6, v206, v236, vcc row_ror:8 row_mask:0xf bank_mask:0xf
	v_cndmask_b32_dpp v7, v207, v237, vcc row_ror:8 row_mask:0xf bank_mask:0xf
	s_add_u32 s14, s14, 0x28000
	s_addc_u32 s15, s15, 0
	s_add_u32 s12, s12, 0x28000
	s_addc_u32 s13, s13, 0
	global_load_dwordx4 v[204:207], v171, s[14:15] nt
	global_load_dwordx4 v[234:237], v171, s[12:13] nt
	v_lshlrev_b32_e32 v246, 16, v0
	v_and_b32_e32 v247, 0xffff0000, v0
	v_pk_fma_f32 v[118:119], v[118:119], v[142:143], v[246:247]
	v_lshlrev_b32_e32 v248, 16, v1
	v_and_b32_e32 v249, 0xffff0000, v1
	v_pk_fma_f32 v[120:121], v[120:121], v[144:145], v[248:249]
	v_lshlrev_b32_e32 v250, 16, v2
	v_and_b32_e32 v251, 0xffff0000, v2
	v_pk_fma_f32 v[114:115], v[114:115], v[150:151], v[250:251]
	v_lshlrev_b32_e32 v208, 16, v3
	v_and_b32_e32 v209, 0xffff0000, v3
	v_pk_fma_f32 v[116:117], v[116:117], v[152:153], v[208:209]
	v_lshlrev_b32_e32 v246, 16, v4
	v_and_b32_e32 v247, 0xffff0000, v4
	v_pk_fma_f32 v[110:111], v[110:111], v[138:139], v[246:247]
	v_lshlrev_b32_e32 v248, 16, v5
	v_and_b32_e32 v249, 0xffff0000, v5
	v_pk_fma_f32 v[112:113], v[112:113], v[140:141], v[248:249]
	v_lshlrev_b32_e32 v250, 16, v6
	v_and_b32_e32 v251, 0xffff0000, v6
	v_pk_fma_f32 v[106:107], v[106:107], v[146:147], v[250:251]
	v_lshlrev_b32_e32 v208, 16, v7
	v_and_b32_e32 v209, 0xffff0000, v7
	v_pk_fma_f32 v[108:109], v[108:109], v[148:149], v[208:209]
	v_cvt_pk_bf16_f32 v0, v118, v119
	v_cvt_pk_bf16_f32 v1, v120, v121
	v_cvt_pk_bf16_f32 v2, v114, v115
	v_cvt_pk_bf16_f32 v3, v116, v117
	v_cvt_pk_bf16_f32 v4, v110, v111
	v_cvt_pk_bf16_f32 v5, v112, v113
	v_cvt_pk_bf16_f32 v6, v106, v107
	v_cvt_pk_bf16_f32 v7, v108, v109
	v_mul_f32_e32 v246, v119, v119
	v_mul_f32_e32 v248, v121, v121
	v_fmac_f32_e32 v246, v118, v118
	v_fmac_f32_e32 v248, v120, v120
	v_add_f32_e32 v246, v246, v248
	v_mul_f32_e32 v248, v115, v115
	v_fmac_f32_e32 v248, v114, v114
	v_add_f32_e32 v246, v246, v248
	v_mul_f32_e32 v248, v117, v117
	v_fmac_f32_e32 v248, v116, v116
	v_add_f32_e32 v246, v248, v246
	v_mul_f32_e32 v247, v111, v111
	v_mul_f32_e32 v248, v113, v113
	v_fmac_f32_e32 v247, v110, v110
	v_fmac_f32_e32 v248, v112, v112
	v_add_f32_e32 v247, v247, v248
	v_mul_f32_e32 v248, v107, v107
	v_fmac_f32_e32 v248, v106, v106
	v_add_f32_e32 v247, v247, v248
	v_mul_f32_e32 v248, v109, v109
	v_fmac_f32_e32 v248, v108, v108
	v_add_f32_e32 v247, v248, v247
	v_add_f32_e32 v246, v246, v247
	v_mov_b32_e32 v247, v246
	s_nop 1
	v_permlane16_swap_b32_e32 v246, v247
	s_nop 1
	v_add_f32_e32 v246, v246, v247
	v_mov_b32_e32 v247, v246
	s_nop 1
	v_permlane32_swap_b32_e32 v246, v247
	v_add_u32_e32 v248, s8, v223
	s_nop 0
	v_add_f32_e32 v246, v246, v247
	s_mov_b64 exec, s[44:45]
	ds_write_b32 v248, v246 offset:256
	s_mov_b64 exec, -1
	v_pk_mul_f32 v[118:119], v[180:181], v[118:119]
	v_pk_mul_f32 v[120:121], v[182:183], v[120:121]
	v_pk_mul_f32 v[114:115], v[184:185], v[114:115]
	v_pk_mul_f32 v[116:117], v[186:187], v[116:117]
	v_pk_mul_f32 v[110:111], v[188:189], v[110:111]
	v_pk_mul_f32 v[112:113], v[190:191], v[112:113]
	v_pk_mul_f32 v[106:107], v[192:193], v[106:107]
	v_pk_mul_f32 v[108:109], v[194:195], v[108:109]
	v_cvt_pk_bf16_f32 v246, v118, v119
	v_cvt_pk_bf16_f32 v247, v120, v121
	v_cvt_pk_bf16_f32 v248, v114, v115
	v_cvt_pk_bf16_f32 v249, v116, v117
	v_cvt_pk_bf16_f32 v250, v110, v111
	v_cvt_pk_bf16_f32 v251, v112, v113
	v_cvt_pk_bf16_f32 v208, v106, v107
	v_cvt_pk_bf16_f32 v209, v108, v109
	s_add_u32 s2, s2, 0x8000
	s_addc_u32 s3, s3, 0
	s_add_u32 s18, s18, 0x8000
	s_addc_u32 s19, s19, 0
	s_add_u32 s78, s78, 0x8000
	s_addc_u32 s79, s79, 0
	s_add_u32 s22, s22, 0x8000
	s_addc_u32 s23, s23, 0
	s_mov_b64 vcc, s[6:7]
	v_cndmask_b32_dpp v118, v4, v0, vcc row_ror:8 row_mask:0xf bank_mask:0xf
	v_cndmask_b32_dpp v119, v5, v1, vcc row_ror:8 row_mask:0xf bank_mask:0xf
	v_cndmask_b32_dpp v120, v6, v2, vcc row_ror:8 row_mask:0xf bank_mask:0xf
	v_cndmask_b32_dpp v121, v7, v3, vcc row_ror:8 row_mask:0xf bank_mask:0xf
	v_cndmask_b32_dpp v110, v250, v246, vcc row_ror:8 row_mask:0xf bank_mask:0xf
	v_cndmask_b32_dpp v111, v251, v247, vcc row_ror:8 row_mask:0xf bank_mask:0xf
	v_cndmask_b32_dpp v112, v208, v248, vcc row_ror:8 row_mask:0xf bank_mask:0xf
	v_cndmask_b32_dpp v113, v209, v249, vcc row_ror:8 row_mask:0xf bank_mask:0xf
	s_not_b64 vcc, s[6:7]
	v_cndmask_b32_dpp v114, v0, v4, vcc row_ror:8 row_mask:0xf bank_mask:0xf
	v_cndmask_b32_dpp v115, v1, v5, vcc row_ror:8 row_mask:0xf bank_mask:0xf
	v_cndmask_b32_dpp v116, v2, v6, vcc row_ror:8 row_mask:0xf bank_mask:0xf
	v_cndmask_b32_dpp v117, v3, v7, vcc row_ror:8 row_mask:0xf bank_mask:0xf
	v_cndmask_b32_dpp v106, v246, v250, vcc row_ror:8 row_mask:0xf bank_mask:0xf
	v_cndmask_b32_dpp v107, v247, v251, vcc row_ror:8 row_mask:0xf bank_mask:0xf
	v_cndmask_b32_dpp v108, v248, v208, vcc row_ror:8 row_mask:0xf bank_mask:0xf
	v_cndmask_b32_dpp v109, v249, v209, vcc row_ror:8 row_mask:0xf bank_mask:0xf
	global_store_dwordx4 v171, v[118:121], s[2:3]
	global_store_dwordx4 v171, v[114:117], s[18:19]
	global_store_dwordx4 v171, v[110:113], s[78:79]
	global_store_dwordx4 v171, v[106:109], s[22:23]
	s_waitcnt vmcnt(12)
	s_mov_b64 vcc, s[6:7]
	v_cndmask_b32_dpp v0, v242, v238, vcc row_ror:8 row_mask:0xf bank_mask:0xf
	v_cndmask_b32_dpp v1, v243, v239, vcc row_ror:8 row_mask:0xf bank_mask:0xf
	v_cndmask_b32_dpp v2, v244, v240, vcc row_ror:8 row_mask:0xf bank_mask:0xf
	v_cndmask_b32_dpp v3, v245, v241, vcc row_ror:8 row_mask:0xf bank_mask:0xf
	s_not_b64 vcc, s[6:7]
	v_cndmask_b32_dpp v4, v238, v242, vcc row_ror:8 row_mask:0xf bank_mask:0xf
	v_cndmask_b32_dpp v5, v239, v243, vcc row_ror:8 row_mask:0xf bank_mask:0xf
	v_cndmask_b32_dpp v6, v240, v244, vcc row_ror:8 row_mask:0xf bank_mask:0xf
	v_cndmask_b32_dpp v7, v241, v245, vcc row_ror:8 row_mask:0xf bank_mask:0xf
	s_add_u32 s14, s14, 0x8000
	s_addc_u32 s15, s15, 0
	s_add_u32 s12, s12, 0x8000
	s_addc_u32 s13, s13, 0
	global_load_dwordx4 v[238:241], v171, s[14:15] nt
	global_load_dwordx4 v[242:245], v171, s[12:13] nt
	v_lshlrev_b32_e32 v246, 16, v0
	v_and_b32_e32 v247, 0xffff0000, v0
	v_pk_fma_f32 v[102:103], v[102:103], v[142:143], v[246:247]
	v_lshlrev_b32_e32 v248, 16, v1
	v_and_b32_e32 v249, 0xffff0000, v1
	v_pk_fma_f32 v[104:105], v[104:105], v[144:145], v[248:249]
	v_lshlrev_b32_e32 v250, 16, v2
	v_and_b32_e32 v251, 0xffff0000, v2
	v_pk_fma_f32 v[98:99], v[98:99], v[150:151], v[250:251]
	v_lshlrev_b32_e32 v208, 16, v3
	v_and_b32_e32 v209, 0xffff0000, v3
	v_pk_fma_f32 v[100:101], v[100:101], v[152:153], v[208:209]
	v_lshlrev_b32_e32 v246, 16, v4
	v_and_b32_e32 v247, 0xffff0000, v4
	v_pk_fma_f32 v[92:93], v[92:93], v[138:139], v[246:247]
	v_lshlrev_b32_e32 v248, 16, v5
	v_and_b32_e32 v249, 0xffff0000, v5
	v_pk_fma_f32 v[94:95], v[94:95], v[140:141], v[248:249]
	v_lshlrev_b32_e32 v250, 16, v6
	v_and_b32_e32 v251, 0xffff0000, v6
	v_pk_fma_f32 v[88:89], v[88:89], v[146:147], v[250:251]
	v_lshlrev_b32_e32 v208, 16, v7
	v_and_b32_e32 v209, 0xffff0000, v7
	v_pk_fma_f32 v[90:91], v[90:91], v[148:149], v[208:209]
	v_cvt_pk_bf16_f32 v0, v102, v103
	v_cvt_pk_bf16_f32 v1, v104, v105
	v_cvt_pk_bf16_f32 v2, v98, v99
	v_cvt_pk_bf16_f32 v3, v100, v101
	v_cvt_pk_bf16_f32 v4, v92, v93
	v_cvt_pk_bf16_f32 v5, v94, v95
	v_cvt_pk_bf16_f32 v6, v88, v89
	v_cvt_pk_bf16_f32 v7, v90, v91
	v_mul_f32_e32 v246, v103, v103
	v_mul_f32_e32 v248, v105, v105
	v_fmac_f32_e32 v246, v102, v102
	v_fmac_f32_e32 v248, v104, v104
	v_add_f32_e32 v246, v246, v248
	v_mul_f32_e32 v248, v99, v99
	v_fmac_f32_e32 v248, v98, v98
	v_add_f32_e32 v246, v246, v248
	v_mul_f32_e32 v248, v101, v101
	v_fmac_f32_e32 v248, v100, v100
	v_add_f32_e32 v246, v248, v246
	v_mul_f32_e32 v247, v93, v93
	v_mul_f32_e32 v248, v95, v95
	v_fmac_f32_e32 v247, v92, v92
	v_fmac_f32_e32 v248, v94, v94
	v_add_f32_e32 v247, v247, v248
	v_mul_f32_e32 v248, v89, v89
	v_fmac_f32_e32 v248, v88, v88
	v_add_f32_e32 v247, v247, v248
	v_mul_f32_e32 v248, v91, v91
	v_fmac_f32_e32 v248, v90, v90
	v_add_f32_e32 v247, v248, v247
	v_add_f32_e32 v246, v246, v247
	v_mov_b32_e32 v247, v246
	s_nop 1
	v_permlane16_swap_b32_e32 v246, v247
	s_nop 1
	v_add_f32_e32 v246, v246, v247
	v_mov_b32_e32 v247, v246
	s_nop 1
	v_permlane32_swap_b32_e32 v246, v247
	v_add_u32_e32 v248, s8, v223
	s_nop 0
	v_add_f32_e32 v246, v246, v247
	s_mov_b64 exec, s[44:45]
	ds_write_b32 v248, v246 offset:512
	s_mov_b64 exec, -1
	v_pk_mul_f32 v[102:103], v[180:181], v[102:103]
	v_pk_mul_f32 v[104:105], v[182:183], v[104:105]
	v_pk_mul_f32 v[98:99], v[184:185], v[98:99]
	v_pk_mul_f32 v[100:101], v[186:187], v[100:101]
	v_pk_mul_f32 v[92:93], v[188:189], v[92:93]
	v_pk_mul_f32 v[94:95], v[190:191], v[94:95]
	v_pk_mul_f32 v[88:89], v[192:193], v[88:89]
	v_pk_mul_f32 v[90:91], v[194:195], v[90:91]
	v_cvt_pk_bf16_f32 v246, v102, v103
	v_cvt_pk_bf16_f32 v247, v104, v105
	v_cvt_pk_bf16_f32 v248, v98, v99
	v_cvt_pk_bf16_f32 v249, v100, v101
	v_cvt_pk_bf16_f32 v250, v92, v93
	v_cvt_pk_bf16_f32 v251, v94, v95
	v_cvt_pk_bf16_f32 v208, v88, v89
	v_cvt_pk_bf16_f32 v209, v90, v91
	s_add_u32 s2, s2, 0x8000
	s_addc_u32 s3, s3, 0
	s_add_u32 s18, s18, 0x8000
	s_addc_u32 s19, s19, 0
	s_add_u32 s78, s78, 0x8000
	s_addc_u32 s79, s79, 0
	s_add_u32 s22, s22, 0x8000
	s_addc_u32 s23, s23, 0
	s_mov_b64 vcc, s[6:7]
	v_cndmask_b32_dpp v102, v4, v0, vcc row_ror:8 row_mask:0xf bank_mask:0xf
	v_cndmask_b32_dpp v103, v5, v1, vcc row_ror:8 row_mask:0xf bank_mask:0xf
	v_cndmask_b32_dpp v104, v6, v2, vcc row_ror:8 row_mask:0xf bank_mask:0xf
	v_cndmask_b32_dpp v105, v7, v3, vcc row_ror:8 row_mask:0xf bank_mask:0xf
	v_cndmask_b32_dpp v92, v250, v246, vcc row_ror:8 row_mask:0xf bank_mask:0xf
	v_cndmask_b32_dpp v93, v251, v247, vcc row_ror:8 row_mask:0xf bank_mask:0xf
	v_cndmask_b32_dpp v94, v208, v248, vcc row_ror:8 row_mask:0xf bank_mask:0xf
	v_cndmask_b32_dpp v95, v209, v249, vcc row_ror:8 row_mask:0xf bank_mask:0xf
	s_not_b64 vcc, s[6:7]
	v_cndmask_b32_dpp v98, v0, v4, vcc row_ror:8 row_mask:0xf bank_mask:0xf
	v_cndmask_b32_dpp v99, v1, v5, vcc row_ror:8 row_mask:0xf bank_mask:0xf
	v_cndmask_b32_dpp v100, v2, v6, vcc row_ror:8 row_mask:0xf bank_mask:0xf
	v_cndmask_b32_dpp v101, v3, v7, vcc row_ror:8 row_mask:0xf bank_mask:0xf
	v_cndmask_b32_dpp v88, v246, v250, vcc row_ror:8 row_mask:0xf bank_mask:0xf
	v_cndmask_b32_dpp v89, v247, v251, vcc row_ror:8 row_mask:0xf bank_mask:0xf
	v_cndmask_b32_dpp v90, v248, v208, vcc row_ror:8 row_mask:0xf bank_mask:0xf
	v_cndmask_b32_dpp v91, v249, v209, vcc row_ror:8 row_mask:0xf bank_mask:0xf
	global_store_dwordx4 v171, v[102:105], s[2:3]
	global_store_dwordx4 v171, v[98:101], s[18:19]
	global_store_dwordx4 v171, v[92:95], s[78:79]
	global_store_dwordx4 v171, v[88:91], s[22:23]
	s_waitcnt vmcnt(16)
	s_mov_b64 vcc, s[6:7]
	v_cndmask_b32_dpp v0, v200, v196, vcc row_ror:8 row_mask:0xf bank_mask:0xf
	v_cndmask_b32_dpp v1, v201, v197, vcc row_ror:8 row_mask:0xf bank_mask:0xf
	v_cndmask_b32_dpp v2, v202, v198, vcc row_ror:8 row_mask:0xf bank_mask:0xf
	v_cndmask_b32_dpp v3, v203, v199, vcc row_ror:8 row_mask:0xf bank_mask:0xf
	s_not_b64 vcc, s[6:7]
	v_cndmask_b32_dpp v4, v196, v200, vcc row_ror:8 row_mask:0xf bank_mask:0xf
	v_cndmask_b32_dpp v5, v197, v201, vcc row_ror:8 row_mask:0xf bank_mask:0xf
	v_cndmask_b32_dpp v6, v198, v202, vcc row_ror:8 row_mask:0xf bank_mask:0xf
	v_cndmask_b32_dpp v7, v199, v203, vcc row_ror:8 row_mask:0xf bank_mask:0xf
	s_add_u32 s14, s14, 0x8000
	s_addc_u32 s15, s15, 0
	s_add_u32 s12, s12, 0x8000
	s_addc_u32 s13, s13, 0
	global_load_dwordx4 v[196:199], v171, s[14:15] nt
	global_load_dwordx4 v[200:203], v171, s[12:13] nt
	v_lshlrev_b32_e32 v246, 16, v0
	v_and_b32_e32 v247, 0xffff0000, v0
	v_pk_fma_f32 v[84:85], v[84:85], v[142:143], v[246:247]
	v_lshlrev_b32_e32 v248, 16, v1
	v_and_b32_e32 v249, 0xffff0000, v1
	v_pk_fma_f32 v[86:87], v[86:87], v[144:145], v[248:249]
	v_lshlrev_b32_e32 v250, 16, v2
	v_and_b32_e32 v251, 0xffff0000, v2
	v_pk_fma_f32 v[80:81], v[80:81], v[150:151], v[250:251]
	v_lshlrev_b32_e32 v208, 16, v3
	v_and_b32_e32 v209, 0xffff0000, v3
	v_pk_fma_f32 v[82:83], v[82:83], v[152:153], v[208:209]
	v_lshlrev_b32_e32 v246, 16, v4
	v_and_b32_e32 v247, 0xffff0000, v4
	v_pk_fma_f32 v[76:77], v[76:77], v[138:139], v[246:247]
	v_lshlrev_b32_e32 v248, 16, v5
	v_and_b32_e32 v249, 0xffff0000, v5
	v_pk_fma_f32 v[78:79], v[78:79], v[140:141], v[248:249]
	v_lshlrev_b32_e32 v250, 16, v6
	v_and_b32_e32 v251, 0xffff0000, v6
	v_pk_fma_f32 v[72:73], v[72:73], v[146:147], v[250:251]
	v_lshlrev_b32_e32 v208, 16, v7
	v_and_b32_e32 v209, 0xffff0000, v7
	v_pk_fma_f32 v[74:75], v[74:75], v[148:149], v[208:209]
	v_cvt_pk_bf16_f32 v0, v84, v85
	v_cvt_pk_bf16_f32 v1, v86, v87
	v_cvt_pk_bf16_f32 v2, v80, v81
	v_cvt_pk_bf16_f32 v3, v82, v83
	v_cvt_pk_bf16_f32 v4, v76, v77
	v_cvt_pk_bf16_f32 v5, v78, v79
	v_cvt_pk_bf16_f32 v6, v72, v73
	v_cvt_pk_bf16_f32 v7, v74, v75
	v_mul_f32_e32 v246, v85, v85
	v_mul_f32_e32 v248, v87, v87
	v_fmac_f32_e32 v246, v84, v84
	v_fmac_f32_e32 v248, v86, v86
	v_add_f32_e32 v246, v246, v248
	v_mul_f32_e32 v248, v81, v81
	v_fmac_f32_e32 v248, v80, v80
	v_add_f32_e32 v246, v246, v248
	v_mul_f32_e32 v248, v83, v83
	v_fmac_f32_e32 v248, v82, v82
	v_add_f32_e32 v246, v248, v246
	v_mul_f32_e32 v247, v77, v77
	v_mul_f32_e32 v248, v79, v79
	v_fmac_f32_e32 v247, v76, v76
	v_fmac_f32_e32 v248, v78, v78
	v_add_f32_e32 v247, v247, v248
	v_mul_f32_e32 v248, v73, v73
	v_fmac_f32_e32 v248, v72, v72
	v_add_f32_e32 v247, v247, v248
	v_mul_f32_e32 v248, v75, v75
	v_fmac_f32_e32 v248, v74, v74
	v_add_f32_e32 v247, v248, v247
	v_add_f32_e32 v246, v246, v247
	v_mov_b32_e32 v247, v246
	s_nop 1
	v_permlane16_swap_b32_e32 v246, v247
	s_nop 1
	v_add_f32_e32 v246, v246, v247
	v_mov_b32_e32 v247, v246
	s_nop 1
	v_permlane32_swap_b32_e32 v246, v247
	v_add_u32_e32 v248, s8, v223
	s_nop 0
	v_add_f32_e32 v246, v246, v247
	s_mov_b64 exec, s[44:45]
	ds_write_b32 v248, v246 offset:768
	s_mov_b64 exec, -1
	v_pk_mul_f32 v[84:85], v[180:181], v[84:85]
	v_pk_mul_f32 v[86:87], v[182:183], v[86:87]
	v_pk_mul_f32 v[80:81], v[184:185], v[80:81]
	v_pk_mul_f32 v[82:83], v[186:187], v[82:83]
	v_pk_mul_f32 v[76:77], v[188:189], v[76:77]
	v_pk_mul_f32 v[78:79], v[190:191], v[78:79]
	v_pk_mul_f32 v[72:73], v[192:193], v[72:73]
	v_pk_mul_f32 v[74:75], v[194:195], v[74:75]
	v_cvt_pk_bf16_f32 v246, v84, v85
	v_cvt_pk_bf16_f32 v247, v86, v87
	v_cvt_pk_bf16_f32 v248, v80, v81
	v_cvt_pk_bf16_f32 v249, v82, v83
	v_cvt_pk_bf16_f32 v250, v76, v77
	v_cvt_pk_bf16_f32 v251, v78, v79
	v_cvt_pk_bf16_f32 v208, v72, v73
	v_cvt_pk_bf16_f32 v209, v74, v75
	s_add_u32 s2, s2, 0x8000
	s_addc_u32 s3, s3, 0
	s_add_u32 s18, s18, 0x8000
	s_addc_u32 s19, s19, 0
	s_add_u32 s78, s78, 0x8000
	s_addc_u32 s79, s79, 0
	s_add_u32 s22, s22, 0x8000
	s_addc_u32 s23, s23, 0
	s_mov_b64 vcc, s[6:7]
	v_cndmask_b32_dpp v84, v4, v0, vcc row_ror:8 row_mask:0xf bank_mask:0xf
	v_cndmask_b32_dpp v85, v5, v1, vcc row_ror:8 row_mask:0xf bank_mask:0xf
	v_cndmask_b32_dpp v86, v6, v2, vcc row_ror:8 row_mask:0xf bank_mask:0xf
	v_cndmask_b32_dpp v87, v7, v3, vcc row_ror:8 row_mask:0xf bank_mask:0xf
	v_cndmask_b32_dpp v76, v250, v246, vcc row_ror:8 row_mask:0xf bank_mask:0xf
	v_cndmask_b32_dpp v77, v251, v247, vcc row_ror:8 row_mask:0xf bank_mask:0xf
	v_cndmask_b32_dpp v78, v208, v248, vcc row_ror:8 row_mask:0xf bank_mask:0xf
	v_cndmask_b32_dpp v79, v209, v249, vcc row_ror:8 row_mask:0xf bank_mask:0xf
	s_not_b64 vcc, s[6:7]
	v_cndmask_b32_dpp v80, v0, v4, vcc row_ror:8 row_mask:0xf bank_mask:0xf
	v_cndmask_b32_dpp v81, v1, v5, vcc row_ror:8 row_mask:0xf bank_mask:0xf
	v_cndmask_b32_dpp v82, v2, v6, vcc row_ror:8 row_mask:0xf bank_mask:0xf
	v_cndmask_b32_dpp v83, v3, v7, vcc row_ror:8 row_mask:0xf bank_mask:0xf
	v_cndmask_b32_dpp v72, v246, v250, vcc row_ror:8 row_mask:0xf bank_mask:0xf
	v_cndmask_b32_dpp v73, v247, v251, vcc row_ror:8 row_mask:0xf bank_mask:0xf
	v_cndmask_b32_dpp v74, v248, v208, vcc row_ror:8 row_mask:0xf bank_mask:0xf
	v_cndmask_b32_dpp v75, v249, v209, vcc row_ror:8 row_mask:0xf bank_mask:0xf
	global_store_dwordx4 v171, v[84:87], s[2:3]
	global_store_dwordx4 v171, v[80:83], s[18:19]
	global_store_dwordx4 v171, v[76:79], s[78:79]
	global_store_dwordx4 v171, v[72:75], s[22:23]
	s_waitcnt vmcnt(16)
	s_mov_b64 vcc, s[6:7]
	v_cndmask_b32_dpp v0, v234, v204, vcc row_ror:8 row_mask:0xf bank_mask:0xf
	v_cndmask_b32_dpp v1, v235, v205, vcc row_ror:8 row_mask:0xf bank_mask:0xf
	v_cndmask_b32_dpp v2, v236, v206, vcc row_ror:8 row_mask:0xf bank_mask:0xf
	v_cndmask_b32_dpp v3, v237, v207, vcc row_ror:8 row_mask:0xf bank_mask:0xf
	s_not_b64 vcc, s[6:7]
	v_cndmask_b32_dpp v4, v204, v234, vcc row_ror:8 row_mask:0xf bank_mask:0xf
	v_cndmask_b32_dpp v5, v205, v235, vcc row_ror:8 row_mask:0xf bank_mask:0xf
	v_cndmask_b32_dpp v6, v206, v236, vcc row_ror:8 row_mask:0xf bank_mask:0xf
	v_cndmask_b32_dpp v7, v207, v237, vcc row_ror:8 row_mask:0xf bank_mask:0xf
	s_add_u32 s14, s14, 0x8000
	s_addc_u32 s15, s15, 0
	s_add_u32 s12, s12, 0x8000
	s_addc_u32 s13, s13, 0
	global_load_dwordx4 v[204:207], v171, s[14:15] nt
	global_load_dwordx4 v[234:237], v171, s[12:13] nt
	v_lshlrev_b32_e32 v246, 16, v0
	v_and_b32_e32 v247, 0xffff0000, v0
	v_pk_fma_f32 v[68:69], v[68:69], v[142:143], v[246:247]
	v_lshlrev_b32_e32 v248, 16, v1
	v_and_b32_e32 v249, 0xffff0000, v1
	v_pk_fma_f32 v[70:71], v[70:71], v[144:145], v[248:249]
	v_lshlrev_b32_e32 v250, 16, v2
	v_and_b32_e32 v251, 0xffff0000, v2
	v_pk_fma_f32 v[64:65], v[64:65], v[150:151], v[250:251]
	v_lshlrev_b32_e32 v208, 16, v3
	v_and_b32_e32 v209, 0xffff0000, v3
	v_pk_fma_f32 v[66:67], v[66:67], v[152:153], v[208:209]
	v_lshlrev_b32_e32 v246, 16, v4
	v_and_b32_e32 v247, 0xffff0000, v4
	v_pk_fma_f32 v[60:61], v[60:61], v[138:139], v[246:247]
	v_lshlrev_b32_e32 v248, 16, v5
	v_and_b32_e32 v249, 0xffff0000, v5
	v_pk_fma_f32 v[62:63], v[62:63], v[140:141], v[248:249]
	v_lshlrev_b32_e32 v250, 16, v6
	v_and_b32_e32 v251, 0xffff0000, v6
	v_pk_fma_f32 v[56:57], v[56:57], v[146:147], v[250:251]
	v_lshlrev_b32_e32 v208, 16, v7
	v_and_b32_e32 v209, 0xffff0000, v7
	v_pk_fma_f32 v[58:59], v[58:59], v[148:149], v[208:209]
	v_cvt_pk_bf16_f32 v0, v68, v69
	v_cvt_pk_bf16_f32 v1, v70, v71
	v_cvt_pk_bf16_f32 v2, v64, v65
	v_cvt_pk_bf16_f32 v3, v66, v67
	v_cvt_pk_bf16_f32 v4, v60, v61
	v_cvt_pk_bf16_f32 v5, v62, v63
	v_cvt_pk_bf16_f32 v6, v56, v57
	v_cvt_pk_bf16_f32 v7, v58, v59
	v_mul_f32_e32 v246, v69, v69
	v_mul_f32_e32 v248, v71, v71
	v_fmac_f32_e32 v246, v68, v68
	v_fmac_f32_e32 v248, v70, v70
	v_add_f32_e32 v246, v246, v248
	v_mul_f32_e32 v248, v65, v65
	v_fmac_f32_e32 v248, v64, v64
	v_add_f32_e32 v246, v246, v248
	v_mul_f32_e32 v248, v67, v67
	v_fmac_f32_e32 v248, v66, v66
	v_add_f32_e32 v246, v248, v246
	v_mul_f32_e32 v247, v61, v61
	v_mul_f32_e32 v248, v63, v63
	v_fmac_f32_e32 v247, v60, v60
	v_fmac_f32_e32 v248, v62, v62
	v_add_f32_e32 v247, v247, v248
	v_mul_f32_e32 v248, v57, v57
	v_fmac_f32_e32 v248, v56, v56
	v_add_f32_e32 v247, v247, v248
	v_mul_f32_e32 v248, v59, v59
	v_fmac_f32_e32 v248, v58, v58
	v_add_f32_e32 v247, v248, v247
	v_add_f32_e32 v246, v246, v247
	v_mov_b32_e32 v247, v246
	s_nop 1
	v_permlane16_swap_b32_e32 v246, v247
	s_nop 1
	v_add_f32_e32 v246, v246, v247
	v_mov_b32_e32 v247, v246
	s_nop 1
	v_permlane32_swap_b32_e32 v246, v247
	v_add_u32_e32 v248, s8, v223
	s_nop 0
	v_add_f32_e32 v246, v246, v247
	s_mov_b64 exec, s[44:45]
	ds_write_b32 v248, v246 offset:2048
	s_mov_b64 exec, -1
	v_pk_mul_f32 v[68:69], v[180:181], v[68:69]
	v_pk_mul_f32 v[70:71], v[182:183], v[70:71]
	v_pk_mul_f32 v[64:65], v[184:185], v[64:65]
	v_pk_mul_f32 v[66:67], v[186:187], v[66:67]
	v_pk_mul_f32 v[60:61], v[188:189], v[60:61]
	v_pk_mul_f32 v[62:63], v[190:191], v[62:63]
	v_pk_mul_f32 v[56:57], v[192:193], v[56:57]
	v_pk_mul_f32 v[58:59], v[194:195], v[58:59]
	v_cvt_pk_bf16_f32 v246, v68, v69
	v_cvt_pk_bf16_f32 v247, v70, v71
	v_cvt_pk_bf16_f32 v248, v64, v65
	v_cvt_pk_bf16_f32 v249, v66, v67
	v_cvt_pk_bf16_f32 v250, v60, v61
	v_cvt_pk_bf16_f32 v251, v62, v63
	v_cvt_pk_bf16_f32 v208, v56, v57
	v_cvt_pk_bf16_f32 v209, v58, v59
	s_add_u32 s2, s2, 0x28000
	s_addc_u32 s3, s3, 0
	s_add_u32 s18, s18, 0x28000
	s_addc_u32 s19, s19, 0
	s_add_u32 s78, s78, 0x28000
	s_addc_u32 s79, s79, 0
	s_add_u32 s22, s22, 0x28000
	s_addc_u32 s23, s23, 0
	s_mov_b64 vcc, s[6:7]
	v_cndmask_b32_dpp v68, v4, v0, vcc row_ror:8 row_mask:0xf bank_mask:0xf
	v_cndmask_b32_dpp v69, v5, v1, vcc row_ror:8 row_mask:0xf bank_mask:0xf
	v_cndmask_b32_dpp v70, v6, v2, vcc row_ror:8 row_mask:0xf bank_mask:0xf
	v_cndmask_b32_dpp v71, v7, v3, vcc row_ror:8 row_mask:0xf bank_mask:0xf
	v_cndmask_b32_dpp v60, v250, v246, vcc row_ror:8 row_mask:0xf bank_mask:0xf
	v_cndmask_b32_dpp v61, v251, v247, vcc row_ror:8 row_mask:0xf bank_mask:0xf
	v_cndmask_b32_dpp v62, v208, v248, vcc row_ror:8 row_mask:0xf bank_mask:0xf
	v_cndmask_b32_dpp v63, v209, v249, vcc row_ror:8 row_mask:0xf bank_mask:0xf
	s_not_b64 vcc, s[6:7]
	v_cndmask_b32_dpp v64, v0, v4, vcc row_ror:8 row_mask:0xf bank_mask:0xf
	v_cndmask_b32_dpp v65, v1, v5, vcc row_ror:8 row_mask:0xf bank_mask:0xf
	v_cndmask_b32_dpp v66, v2, v6, vcc row_ror:8 row_mask:0xf bank_mask:0xf
	v_cndmask_b32_dpp v67, v3, v7, vcc row_ror:8 row_mask:0xf bank_mask:0xf
	v_cndmask_b32_dpp v56, v246, v250, vcc row_ror:8 row_mask:0xf bank_mask:0xf
	v_cndmask_b32_dpp v57, v247, v251, vcc row_ror:8 row_mask:0xf bank_mask:0xf
	v_cndmask_b32_dpp v58, v248, v208, vcc row_ror:8 row_mask:0xf bank_mask:0xf
	v_cndmask_b32_dpp v59, v249, v209, vcc row_ror:8 row_mask:0xf bank_mask:0xf
	global_store_dwordx4 v171, v[68:71], s[2:3]
	global_store_dwordx4 v171, v[64:67], s[18:19]
	global_store_dwordx4 v171, v[60:63], s[78:79]
	global_store_dwordx4 v171, v[56:59], s[22:23]
	s_waitcnt vmcnt(16)
	s_mov_b64 vcc, s[6:7]
	v_cndmask_b32_dpp v0, v242, v238, vcc row_ror:8 row_mask:0xf bank_mask:0xf
	v_cndmask_b32_dpp v1, v243, v239, vcc row_ror:8 row_mask:0xf bank_mask:0xf
	v_cndmask_b32_dpp v2, v244, v240, vcc row_ror:8 row_mask:0xf bank_mask:0xf
	v_cndmask_b32_dpp v3, v245, v241, vcc row_ror:8 row_mask:0xf bank_mask:0xf
	s_not_b64 vcc, s[6:7]
	v_cndmask_b32_dpp v4, v238, v242, vcc row_ror:8 row_mask:0xf bank_mask:0xf
	v_cndmask_b32_dpp v5, v239, v243, vcc row_ror:8 row_mask:0xf bank_mask:0xf
	v_cndmask_b32_dpp v6, v240, v244, vcc row_ror:8 row_mask:0xf bank_mask:0xf
	v_cndmask_b32_dpp v7, v241, v245, vcc row_ror:8 row_mask:0xf bank_mask:0xf
	v_lshlrev_b32_e32 v246, 16, v0
	v_and_b32_e32 v247, 0xffff0000, v0
	v_pk_fma_f32 v[52:53], v[52:53], v[142:143], v[246:247]
	v_lshlrev_b32_e32 v248, 16, v1
	v_and_b32_e32 v249, 0xffff0000, v1
	v_pk_fma_f32 v[54:55], v[54:55], v[144:145], v[248:249]
	v_lshlrev_b32_e32 v250, 16, v2
	v_and_b32_e32 v251, 0xffff0000, v2
	v_pk_fma_f32 v[48:49], v[48:49], v[150:151], v[250:251]
	v_lshlrev_b32_e32 v208, 16, v3
	v_and_b32_e32 v209, 0xffff0000, v3
	v_pk_fma_f32 v[50:51], v[50:51], v[152:153], v[208:209]
	v_lshlrev_b32_e32 v246, 16, v4
	v_and_b32_e32 v247, 0xffff0000, v4
	v_pk_fma_f32 v[44:45], v[44:45], v[138:139], v[246:247]
	v_lshlrev_b32_e32 v248, 16, v5
	v_and_b32_e32 v249, 0xffff0000, v5
	v_pk_fma_f32 v[46:47], v[46:47], v[140:141], v[248:249]
	v_lshlrev_b32_e32 v250, 16, v6
	v_and_b32_e32 v251, 0xffff0000, v6
	v_pk_fma_f32 v[40:41], v[40:41], v[146:147], v[250:251]
	v_lshlrev_b32_e32 v208, 16, v7
	v_and_b32_e32 v209, 0xffff0000, v7
	v_pk_fma_f32 v[42:43], v[42:43], v[148:149], v[208:209]
	v_cvt_pk_bf16_f32 v0, v52, v53
	v_cvt_pk_bf16_f32 v1, v54, v55
	v_cvt_pk_bf16_f32 v2, v48, v49
	v_cvt_pk_bf16_f32 v3, v50, v51
	v_cvt_pk_bf16_f32 v4, v44, v45
	v_cvt_pk_bf16_f32 v5, v46, v47
	v_cvt_pk_bf16_f32 v6, v40, v41
	v_cvt_pk_bf16_f32 v7, v42, v43
	v_mul_f32_e32 v246, v53, v53
	v_mul_f32_e32 v248, v55, v55
	v_fmac_f32_e32 v246, v52, v52
	v_fmac_f32_e32 v248, v54, v54
	v_add_f32_e32 v246, v246, v248
	v_mul_f32_e32 v248, v49, v49
	v_fmac_f32_e32 v248, v48, v48
	v_add_f32_e32 v246, v246, v248
	v_mul_f32_e32 v248, v51, v51
	v_fmac_f32_e32 v248, v50, v50
	v_add_f32_e32 v246, v248, v246
	v_mul_f32_e32 v247, v45, v45
	v_mul_f32_e32 v248, v47, v47
	v_fmac_f32_e32 v247, v44, v44
	v_fmac_f32_e32 v248, v46, v46
	v_add_f32_e32 v247, v247, v248
	v_mul_f32_e32 v248, v41, v41
	v_fmac_f32_e32 v248, v40, v40
	v_add_f32_e32 v247, v247, v248
	v_mul_f32_e32 v248, v43, v43
	v_fmac_f32_e32 v248, v42, v42
	v_add_f32_e32 v247, v248, v247
	v_add_f32_e32 v246, v246, v247
	v_mov_b32_e32 v247, v246
	s_nop 1
	v_permlane16_swap_b32_e32 v246, v247
	s_nop 1
	v_add_f32_e32 v246, v246, v247
	v_mov_b32_e32 v247, v246
	s_nop 1
	v_permlane32_swap_b32_e32 v246, v247
	v_add_u32_e32 v248, s8, v223
	s_nop 0
	v_add_f32_e32 v246, v246, v247
	s_mov_b64 exec, s[44:45]
	ds_write_b32 v248, v246 offset:2304
	s_mov_b64 exec, -1
	v_pk_mul_f32 v[52:53], v[180:181], v[52:53]
	v_pk_mul_f32 v[54:55], v[182:183], v[54:55]
	v_pk_mul_f32 v[48:49], v[184:185], v[48:49]
	v_pk_mul_f32 v[50:51], v[186:187], v[50:51]
	v_pk_mul_f32 v[44:45], v[188:189], v[44:45]
	v_pk_mul_f32 v[46:47], v[190:191], v[46:47]
	v_pk_mul_f32 v[40:41], v[192:193], v[40:41]
	v_pk_mul_f32 v[42:43], v[194:195], v[42:43]
	v_cvt_pk_bf16_f32 v246, v52, v53
	v_cvt_pk_bf16_f32 v247, v54, v55
	v_cvt_pk_bf16_f32 v248, v48, v49
	v_cvt_pk_bf16_f32 v249, v50, v51
	v_cvt_pk_bf16_f32 v250, v44, v45
	v_cvt_pk_bf16_f32 v251, v46, v47
	v_cvt_pk_bf16_f32 v208, v40, v41
	v_cvt_pk_bf16_f32 v209, v42, v43
	s_add_u32 s2, s2, 0x8000
	s_addc_u32 s3, s3, 0
	s_add_u32 s18, s18, 0x8000
	s_addc_u32 s19, s19, 0
	s_add_u32 s78, s78, 0x8000
	s_addc_u32 s79, s79, 0
	s_add_u32 s22, s22, 0x8000
	s_addc_u32 s23, s23, 0
	s_mov_b64 vcc, s[6:7]
	v_cndmask_b32_dpp v52, v4, v0, vcc row_ror:8 row_mask:0xf bank_mask:0xf
	v_cndmask_b32_dpp v53, v5, v1, vcc row_ror:8 row_mask:0xf bank_mask:0xf
	v_cndmask_b32_dpp v54, v6, v2, vcc row_ror:8 row_mask:0xf bank_mask:0xf
	v_cndmask_b32_dpp v55, v7, v3, vcc row_ror:8 row_mask:0xf bank_mask:0xf
	v_cndmask_b32_dpp v44, v250, v246, vcc row_ror:8 row_mask:0xf bank_mask:0xf
	v_cndmask_b32_dpp v45, v251, v247, vcc row_ror:8 row_mask:0xf bank_mask:0xf
	v_cndmask_b32_dpp v46, v208, v248, vcc row_ror:8 row_mask:0xf bank_mask:0xf
	v_cndmask_b32_dpp v47, v209, v249, vcc row_ror:8 row_mask:0xf bank_mask:0xf
	s_not_b64 vcc, s[6:7]
	v_cndmask_b32_dpp v48, v0, v4, vcc row_ror:8 row_mask:0xf bank_mask:0xf
	v_cndmask_b32_dpp v49, v1, v5, vcc row_ror:8 row_mask:0xf bank_mask:0xf
	v_cndmask_b32_dpp v50, v2, v6, vcc row_ror:8 row_mask:0xf bank_mask:0xf
	v_cndmask_b32_dpp v51, v3, v7, vcc row_ror:8 row_mask:0xf bank_mask:0xf
	v_cndmask_b32_dpp v40, v246, v250, vcc row_ror:8 row_mask:0xf bank_mask:0xf
	v_cndmask_b32_dpp v41, v247, v251, vcc row_ror:8 row_mask:0xf bank_mask:0xf
	v_cndmask_b32_dpp v42, v248, v208, vcc row_ror:8 row_mask:0xf bank_mask:0xf
	v_cndmask_b32_dpp v43, v249, v209, vcc row_ror:8 row_mask:0xf bank_mask:0xf
	global_store_dwordx4 v171, v[52:55], s[2:3]
	global_store_dwordx4 v171, v[48:51], s[18:19]
	global_store_dwordx4 v171, v[44:47], s[78:79]
	global_store_dwordx4 v171, v[40:43], s[22:23]
	s_waitcnt vmcnt(14)
	s_mov_b64 vcc, s[6:7]
	v_cndmask_b32_dpp v0, v200, v196, vcc row_ror:8 row_mask:0xf bank_mask:0xf
	v_cndmask_b32_dpp v1, v201, v197, vcc row_ror:8 row_mask:0xf bank_mask:0xf
	v_cndmask_b32_dpp v2, v202, v198, vcc row_ror:8 row_mask:0xf bank_mask:0xf
	v_cndmask_b32_dpp v3, v203, v199, vcc row_ror:8 row_mask:0xf bank_mask:0xf
	s_not_b64 vcc, s[6:7]
	v_cndmask_b32_dpp v4, v196, v200, vcc row_ror:8 row_mask:0xf bank_mask:0xf
	v_cndmask_b32_dpp v5, v197, v201, vcc row_ror:8 row_mask:0xf bank_mask:0xf
	v_cndmask_b32_dpp v6, v198, v202, vcc row_ror:8 row_mask:0xf bank_mask:0xf
	v_cndmask_b32_dpp v7, v199, v203, vcc row_ror:8 row_mask:0xf bank_mask:0xf
	v_lshlrev_b32_e32 v246, 16, v0
	v_and_b32_e32 v247, 0xffff0000, v0
	v_pk_fma_f32 v[36:37], v[36:37], v[142:143], v[246:247]
	v_lshlrev_b32_e32 v248, 16, v1
	v_and_b32_e32 v249, 0xffff0000, v1
	v_pk_fma_f32 v[38:39], v[38:39], v[144:145], v[248:249]
	v_lshlrev_b32_e32 v250, 16, v2
	v_and_b32_e32 v251, 0xffff0000, v2
	v_pk_fma_f32 v[32:33], v[32:33], v[150:151], v[250:251]
	v_lshlrev_b32_e32 v208, 16, v3
	v_and_b32_e32 v209, 0xffff0000, v3
	v_pk_fma_f32 v[34:35], v[34:35], v[152:153], v[208:209]
	v_lshlrev_b32_e32 v246, 16, v4
	v_and_b32_e32 v247, 0xffff0000, v4
	v_pk_fma_f32 v[28:29], v[28:29], v[138:139], v[246:247]
	v_lshlrev_b32_e32 v248, 16, v5
	v_and_b32_e32 v249, 0xffff0000, v5
	v_pk_fma_f32 v[30:31], v[30:31], v[140:141], v[248:249]
	v_lshlrev_b32_e32 v250, 16, v6
	v_and_b32_e32 v251, 0xffff0000, v6
	v_pk_fma_f32 v[24:25], v[24:25], v[146:147], v[250:251]
	v_lshlrev_b32_e32 v208, 16, v7
	v_and_b32_e32 v209, 0xffff0000, v7
	v_pk_fma_f32 v[26:27], v[26:27], v[148:149], v[208:209]
	v_cvt_pk_bf16_f32 v0, v36, v37
	v_cvt_pk_bf16_f32 v1, v38, v39
	v_cvt_pk_bf16_f32 v2, v32, v33
	v_cvt_pk_bf16_f32 v3, v34, v35
	v_cvt_pk_bf16_f32 v4, v28, v29
	v_cvt_pk_bf16_f32 v5, v30, v31
	v_cvt_pk_bf16_f32 v6, v24, v25
	v_cvt_pk_bf16_f32 v7, v26, v27
	v_mul_f32_e32 v246, v37, v37
	v_mul_f32_e32 v248, v39, v39
	v_fmac_f32_e32 v246, v36, v36
	v_fmac_f32_e32 v248, v38, v38
	v_add_f32_e32 v246, v246, v248
	v_mul_f32_e32 v248, v33, v33
	v_fmac_f32_e32 v248, v32, v32
	v_add_f32_e32 v246, v246, v248
	v_mul_f32_e32 v248, v35, v35
	v_fmac_f32_e32 v248, v34, v34
	v_add_f32_e32 v246, v248, v246
	v_mul_f32_e32 v247, v29, v29
	v_mul_f32_e32 v248, v31, v31
	v_fmac_f32_e32 v247, v28, v28
	v_fmac_f32_e32 v248, v30, v30
	v_add_f32_e32 v247, v247, v248
	v_mul_f32_e32 v248, v25, v25
	v_fmac_f32_e32 v248, v24, v24
	v_add_f32_e32 v247, v247, v248
	v_mul_f32_e32 v248, v27, v27
	v_fmac_f32_e32 v248, v26, v26
	v_add_f32_e32 v247, v248, v247
	v_add_f32_e32 v246, v246, v247
	v_mov_b32_e32 v247, v246
	s_nop 1
	v_permlane16_swap_b32_e32 v246, v247
	s_nop 1
	v_add_f32_e32 v246, v246, v247
	v_mov_b32_e32 v247, v246
	s_nop 1
	v_permlane32_swap_b32_e32 v246, v247
	v_add_u32_e32 v248, s8, v223
	s_nop 0
	v_add_f32_e32 v246, v246, v247
	s_mov_b64 exec, s[44:45]
	ds_write_b32 v248, v246 offset:2560
	s_mov_b64 exec, -1
	v_pk_mul_f32 v[36:37], v[180:181], v[36:37]
	v_pk_mul_f32 v[38:39], v[182:183], v[38:39]
	v_pk_mul_f32 v[32:33], v[184:185], v[32:33]
	v_pk_mul_f32 v[34:35], v[186:187], v[34:35]
	v_pk_mul_f32 v[28:29], v[188:189], v[28:29]
	v_pk_mul_f32 v[30:31], v[190:191], v[30:31]
	v_pk_mul_f32 v[24:25], v[192:193], v[24:25]
	v_pk_mul_f32 v[26:27], v[194:195], v[26:27]
	v_cvt_pk_bf16_f32 v246, v36, v37
	v_cvt_pk_bf16_f32 v247, v38, v39
	v_cvt_pk_bf16_f32 v248, v32, v33
	v_cvt_pk_bf16_f32 v249, v34, v35
	v_cvt_pk_bf16_f32 v250, v28, v29
	v_cvt_pk_bf16_f32 v251, v30, v31
	v_cvt_pk_bf16_f32 v208, v24, v25
	v_cvt_pk_bf16_f32 v209, v26, v27
	s_add_u32 s2, s2, 0x8000
	s_addc_u32 s3, s3, 0
	s_add_u32 s18, s18, 0x8000
	s_addc_u32 s19, s19, 0
	s_add_u32 s78, s78, 0x8000
	s_addc_u32 s79, s79, 0
	s_add_u32 s22, s22, 0x8000
	s_addc_u32 s23, s23, 0
	s_mov_b64 vcc, s[6:7]
	v_cndmask_b32_dpp v36, v4, v0, vcc row_ror:8 row_mask:0xf bank_mask:0xf
	v_cndmask_b32_dpp v37, v5, v1, vcc row_ror:8 row_mask:0xf bank_mask:0xf
	v_cndmask_b32_dpp v38, v6, v2, vcc row_ror:8 row_mask:0xf bank_mask:0xf
	v_cndmask_b32_dpp v39, v7, v3, vcc row_ror:8 row_mask:0xf bank_mask:0xf
	v_cndmask_b32_dpp v28, v250, v246, vcc row_ror:8 row_mask:0xf bank_mask:0xf
	v_cndmask_b32_dpp v29, v251, v247, vcc row_ror:8 row_mask:0xf bank_mask:0xf
	v_cndmask_b32_dpp v30, v208, v248, vcc row_ror:8 row_mask:0xf bank_mask:0xf
	v_cndmask_b32_dpp v31, v209, v249, vcc row_ror:8 row_mask:0xf bank_mask:0xf
	s_not_b64 vcc, s[6:7]
	v_cndmask_b32_dpp v32, v0, v4, vcc row_ror:8 row_mask:0xf bank_mask:0xf
	v_cndmask_b32_dpp v33, v1, v5, vcc row_ror:8 row_mask:0xf bank_mask:0xf
	v_cndmask_b32_dpp v34, v2, v6, vcc row_ror:8 row_mask:0xf bank_mask:0xf
	v_cndmask_b32_dpp v35, v3, v7, vcc row_ror:8 row_mask:0xf bank_mask:0xf
	v_cndmask_b32_dpp v24, v246, v250, vcc row_ror:8 row_mask:0xf bank_mask:0xf
	v_cndmask_b32_dpp v25, v247, v251, vcc row_ror:8 row_mask:0xf bank_mask:0xf
	v_cndmask_b32_dpp v26, v248, v208, vcc row_ror:8 row_mask:0xf bank_mask:0xf
	v_cndmask_b32_dpp v27, v249, v209, vcc row_ror:8 row_mask:0xf bank_mask:0xf
	global_store_dwordx4 v171, v[36:39], s[2:3]
	global_store_dwordx4 v171, v[32:35], s[18:19]
	global_store_dwordx4 v171, v[28:31], s[78:79]
	global_store_dwordx4 v171, v[24:27], s[22:23]
	s_waitcnt vmcnt(12)
	s_mov_b64 vcc, s[6:7]
	v_cndmask_b32_dpp v0, v234, v204, vcc row_ror:8 row_mask:0xf bank_mask:0xf
	v_cndmask_b32_dpp v1, v235, v205, vcc row_ror:8 row_mask:0xf bank_mask:0xf
	v_cndmask_b32_dpp v2, v236, v206, vcc row_ror:8 row_mask:0xf bank_mask:0xf
	v_cndmask_b32_dpp v3, v237, v207, vcc row_ror:8 row_mask:0xf bank_mask:0xf
	s_not_b64 vcc, s[6:7]
	v_cndmask_b32_dpp v4, v204, v234, vcc row_ror:8 row_mask:0xf bank_mask:0xf
	v_cndmask_b32_dpp v5, v205, v235, vcc row_ror:8 row_mask:0xf bank_mask:0xf
	v_cndmask_b32_dpp v6, v206, v236, vcc row_ror:8 row_mask:0xf bank_mask:0xf
	v_cndmask_b32_dpp v7, v207, v237, vcc row_ror:8 row_mask:0xf bank_mask:0xf
	v_lshlrev_b32_e32 v246, 16, v0
	v_and_b32_e32 v247, 0xffff0000, v0
	v_pk_fma_f32 v[20:21], v[20:21], v[142:143], v[246:247]
	v_lshlrev_b32_e32 v248, 16, v1
	v_and_b32_e32 v249, 0xffff0000, v1
	v_pk_fma_f32 v[22:23], v[22:23], v[144:145], v[248:249]
	v_lshlrev_b32_e32 v250, 16, v2
	v_and_b32_e32 v251, 0xffff0000, v2
	v_pk_fma_f32 v[16:17], v[16:17], v[150:151], v[250:251]
	v_lshlrev_b32_e32 v208, 16, v3
	v_and_b32_e32 v209, 0xffff0000, v3
	v_pk_fma_f32 v[18:19], v[18:19], v[152:153], v[208:209]
	v_lshlrev_b32_e32 v246, 16, v4
	v_and_b32_e32 v247, 0xffff0000, v4
	v_pk_fma_f32 v[12:13], v[12:13], v[138:139], v[246:247]
	v_lshlrev_b32_e32 v248, 16, v5
	v_and_b32_e32 v249, 0xffff0000, v5
	v_pk_fma_f32 v[14:15], v[14:15], v[140:141], v[248:249]
	v_lshlrev_b32_e32 v250, 16, v6
	v_and_b32_e32 v251, 0xffff0000, v6
	v_pk_fma_f32 v[8:9], v[8:9], v[146:147], v[250:251]
	v_lshlrev_b32_e32 v208, 16, v7
	v_and_b32_e32 v209, 0xffff0000, v7
	v_pk_fma_f32 v[10:11], v[10:11], v[148:149], v[208:209]
	v_cvt_pk_bf16_f32 v0, v20, v21
	v_cvt_pk_bf16_f32 v1, v22, v23
	v_cvt_pk_bf16_f32 v2, v16, v17
	v_cvt_pk_bf16_f32 v3, v18, v19
	v_cvt_pk_bf16_f32 v4, v12, v13
	v_cvt_pk_bf16_f32 v5, v14, v15
	v_cvt_pk_bf16_f32 v6, v8, v9
	v_cvt_pk_bf16_f32 v7, v10, v11
	v_mul_f32_e32 v246, v21, v21
	v_mul_f32_e32 v248, v23, v23
	v_fmac_f32_e32 v246, v20, v20
	v_fmac_f32_e32 v248, v22, v22
	v_add_f32_e32 v246, v246, v248
	v_mul_f32_e32 v248, v17, v17
	v_fmac_f32_e32 v248, v16, v16
	v_add_f32_e32 v246, v246, v248
	v_mul_f32_e32 v248, v19, v19
	v_fmac_f32_e32 v248, v18, v18
	v_add_f32_e32 v246, v248, v246
	v_mul_f32_e32 v247, v13, v13
	v_mul_f32_e32 v248, v15, v15
	v_fmac_f32_e32 v247, v12, v12
	v_fmac_f32_e32 v248, v14, v14
	v_add_f32_e32 v247, v247, v248
	v_mul_f32_e32 v248, v9, v9
	v_fmac_f32_e32 v248, v8, v8
	v_add_f32_e32 v247, v247, v248
	v_mul_f32_e32 v248, v11, v11
	v_fmac_f32_e32 v248, v10, v10
	v_add_f32_e32 v247, v248, v247
	v_add_f32_e32 v246, v246, v247
	v_mov_b32_e32 v247, v246
	s_nop 1
	v_permlane16_swap_b32_e32 v246, v247
	s_nop 1
	v_add_f32_e32 v246, v246, v247
	v_mov_b32_e32 v247, v246
	s_nop 1
	v_permlane32_swap_b32_e32 v246, v247
	v_add_u32_e32 v248, s8, v223
	s_nop 0
	v_add_f32_e32 v246, v246, v247
	s_mov_b64 exec, s[44:45]
	ds_write_b32 v248, v246 offset:2816
	s_mov_b64 exec, -1
	v_pk_mul_f32 v[20:21], v[180:181], v[20:21]
	v_pk_mul_f32 v[22:23], v[182:183], v[22:23]
	v_pk_mul_f32 v[16:17], v[184:185], v[16:17]
	v_pk_mul_f32 v[18:19], v[186:187], v[18:19]
	v_pk_mul_f32 v[12:13], v[188:189], v[12:13]
	v_pk_mul_f32 v[14:15], v[190:191], v[14:15]
	v_pk_mul_f32 v[8:9], v[192:193], v[8:9]
	v_pk_mul_f32 v[10:11], v[194:195], v[10:11]
	v_cvt_pk_bf16_f32 v246, v20, v21
	v_cvt_pk_bf16_f32 v247, v22, v23
	v_cvt_pk_bf16_f32 v248, v16, v17
	v_cvt_pk_bf16_f32 v249, v18, v19
	v_cvt_pk_bf16_f32 v250, v12, v13
	v_cvt_pk_bf16_f32 v251, v14, v15
	v_cvt_pk_bf16_f32 v208, v8, v9
	v_cvt_pk_bf16_f32 v209, v10, v11
	s_add_u32 s2, s2, 0x8000
	s_addc_u32 s3, s3, 0
	s_add_u32 s18, s18, 0x8000
	s_addc_u32 s19, s19, 0
	s_add_u32 s78, s78, 0x8000
	s_addc_u32 s79, s79, 0
	s_add_u32 s22, s22, 0x8000
	s_addc_u32 s23, s23, 0
	s_mov_b64 vcc, s[6:7]
	v_cndmask_b32_dpp v20, v4, v0, vcc row_ror:8 row_mask:0xf bank_mask:0xf
	v_cndmask_b32_dpp v21, v5, v1, vcc row_ror:8 row_mask:0xf bank_mask:0xf
	v_cndmask_b32_dpp v22, v6, v2, vcc row_ror:8 row_mask:0xf bank_mask:0xf
	v_cndmask_b32_dpp v23, v7, v3, vcc row_ror:8 row_mask:0xf bank_mask:0xf
	v_cndmask_b32_dpp v12, v250, v246, vcc row_ror:8 row_mask:0xf bank_mask:0xf
	v_cndmask_b32_dpp v13, v251, v247, vcc row_ror:8 row_mask:0xf bank_mask:0xf
	v_cndmask_b32_dpp v14, v208, v248, vcc row_ror:8 row_mask:0xf bank_mask:0xf
	v_cndmask_b32_dpp v15, v209, v249, vcc row_ror:8 row_mask:0xf bank_mask:0xf
	s_not_b64 vcc, s[6:7]
	v_cndmask_b32_dpp v16, v0, v4, vcc row_ror:8 row_mask:0xf bank_mask:0xf
	v_cndmask_b32_dpp v17, v1, v5, vcc row_ror:8 row_mask:0xf bank_mask:0xf
	v_cndmask_b32_dpp v18, v2, v6, vcc row_ror:8 row_mask:0xf bank_mask:0xf
	v_cndmask_b32_dpp v19, v3, v7, vcc row_ror:8 row_mask:0xf bank_mask:0xf
	v_cndmask_b32_dpp v8, v246, v250, vcc row_ror:8 row_mask:0xf bank_mask:0xf
	v_cndmask_b32_dpp v9, v247, v251, vcc row_ror:8 row_mask:0xf bank_mask:0xf
	v_cndmask_b32_dpp v10, v248, v208, vcc row_ror:8 row_mask:0xf bank_mask:0xf
	v_cndmask_b32_dpp v11, v249, v209, vcc row_ror:8 row_mask:0xf bank_mask:0xf
	global_store_dwordx4 v171, v[20:23], s[2:3]
	global_store_dwordx4 v171, v[16:19], s[18:19]
	global_store_dwordx4 v171, v[12:15], s[78:79]
	global_store_dwordx4 v171, v[8:11], s[22:23]
	s_mov_b32 s100, 1
	s_branch .LBB0_714
.Lfo_nong:
	global_load_dwordx4 v[142:145], v170, s[16:17]
	global_load_dwordx4 v[150:153], v170, s[16:17] offset:16
	global_load_dwordx4 v[138:141], v170, s[16:17] offset:128
	global_load_dwordx4 v[146:149], v170, s[16:17] offset:144
	global_load_dwordx4 v[196:199], v171, s[14:15] nt
	global_load_dwordx4 v[200:203], v171, s[12:13] nt
	s_add_u32 s14, s14, 0x8000
	s_addc_u32 s15, s15, 0
	s_add_u32 s12, s12, 0x8000
	s_addc_u32 s13, s13, 0
	global_load_dwordx4 v[204:207], v171, s[14:15] nt
	global_load_dwordx4 v[234:237], v171, s[12:13] nt
	s_add_u32 s14, s14, 0x8000
	s_addc_u32 s15, s15, 0
	s_add_u32 s12, s12, 0x8000
	s_addc_u32 s13, s13, 0
	global_load_dwordx4 v[238:241], v171, s[14:15] nt
	global_load_dwordx4 v[242:245], v171, s[12:13] nt
	s_waitcnt vmcnt(4)
	s_mov_b64 vcc, s[6:7]
	v_cndmask_b32_dpp v0, v200, v196, vcc row_ror:8 row_mask:0xf bank_mask:0xf
	v_cndmask_b32_dpp v1, v201, v197, vcc row_ror:8 row_mask:0xf bank_mask:0xf
	v_cndmask_b32_dpp v2, v202, v198, vcc row_ror:8 row_mask:0xf bank_mask:0xf
	v_cndmask_b32_dpp v3, v203, v199, vcc row_ror:8 row_mask:0xf bank_mask:0xf
	s_not_b64 vcc, s[6:7]
	v_cndmask_b32_dpp v4, v196, v200, vcc row_ror:8 row_mask:0xf bank_mask:0xf
	v_cndmask_b32_dpp v5, v197, v201, vcc row_ror:8 row_mask:0xf bank_mask:0xf
	v_cndmask_b32_dpp v6, v198, v202, vcc row_ror:8 row_mask:0xf bank_mask:0xf
	v_cndmask_b32_dpp v7, v199, v203, vcc row_ror:8 row_mask:0xf bank_mask:0xf
	s_add_u32 s14, s14, 0x8000
	s_addc_u32 s15, s15, 0
	s_add_u32 s12, s12, 0x8000
	s_addc_u32 s13, s13, 0
	global_load_dwordx4 v[196:199], v171, s[14:15] nt
	global_load_dwordx4 v[200:203], v171, s[12:13] nt
	v_lshlrev_b32_e32 v246, 16, v0
	v_and_b32_e32 v247, 0xffff0000, v0
	v_pk_fma_f32 v[134:135], v[134:135], v[142:143], v[246:247]
	v_lshlrev_b32_e32 v248, 16, v1
	v_and_b32_e32 v249, 0xffff0000, v1
	v_pk_fma_f32 v[136:137], v[136:137], v[144:145], v[248:249]
	v_lshlrev_b32_e32 v250, 16, v2
	v_and_b32_e32 v251, 0xffff0000, v2
	v_pk_fma_f32 v[130:131], v[130:131], v[150:151], v[250:251]
	v_lshlrev_b32_e32 v208, 16, v3
	v_and_b32_e32 v209, 0xffff0000, v3
	v_pk_fma_f32 v[132:133], v[132:133], v[152:153], v[208:209]
	v_lshlrev_b32_e32 v246, 16, v4
	v_and_b32_e32 v247, 0xffff0000, v4
	v_pk_fma_f32 v[126:127], v[126:127], v[138:139], v[246:247]
	v_lshlrev_b32_e32 v248, 16, v5
	v_and_b32_e32 v249, 0xffff0000, v5
	v_pk_fma_f32 v[128:129], v[128:129], v[140:141], v[248:249]
	v_lshlrev_b32_e32 v250, 16, v6
	v_and_b32_e32 v251, 0xffff0000, v6
	v_pk_fma_f32 v[122:123], v[122:123], v[146:147], v[250:251]
	v_lshlrev_b32_e32 v208, 16, v7
	v_and_b32_e32 v209, 0xffff0000, v7
	v_pk_fma_f32 v[124:125], v[124:125], v[148:149], v[208:209]
	v_cvt_pk_bf16_f32 v0, v134, v135
	v_cvt_pk_bf16_f32 v1, v136, v137
	v_cvt_pk_bf16_f32 v2, v130, v131
	v_cvt_pk_bf16_f32 v3, v132, v133
	v_cvt_pk_bf16_f32 v4, v126, v127
	v_cvt_pk_bf16_f32 v5, v128, v129
	v_cvt_pk_bf16_f32 v6, v122, v123
	v_cvt_pk_bf16_f32 v7, v124, v125
	v_mul_f32_e32 v246, v135, v135
	v_mul_f32_e32 v248, v137, v137
	v_fmac_f32_e32 v246, v134, v134
	v_fmac_f32_e32 v248, v136, v136
	v_add_f32_e32 v246, v246, v248
	v_mul_f32_e32 v248, v131, v131
	v_fmac_f32_e32 v248, v130, v130
	v_add_f32_e32 v246, v246, v248
	v_mul_f32_e32 v248, v133, v133
	v_fmac_f32_e32 v248, v132, v132
	v_add_f32_e32 v246, v248, v246
	v_mul_f32_e32 v247, v127, v127
	v_mul_f32_e32 v248, v129, v129
	v_fmac_f32_e32 v247, v126, v126
	v_fmac_f32_e32 v248, v128, v128
	v_add_f32_e32 v247, v247, v248
	v_mul_f32_e32 v248, v123, v123
	v_fmac_f32_e32 v248, v122, v122
	v_add_f32_e32 v247, v247, v248
	v_mul_f32_e32 v248, v125, v125
	v_fmac_f32_e32 v248, v124, v124
	v_add_f32_e32 v247, v248, v247
	v_add_f32_e32 v246, v246, v247
	v_mov_b32_e32 v247, v246
	s_nop 1
	v_permlane16_swap_b32_e32 v246, v247
	s_nop 1
	v_add_f32_e32 v246, v246, v247
	v_mov_b32_e32 v247, v246
	s_nop 1
	v_permlane32_swap_b32_e32 v246, v247
	v_add_u32_e32 v248, s8, v223
	s_nop 0
	v_add_f32_e32 v246, v246, v247
	s_mov_b64 exec, s[44:45]
	ds_write_b32 v248, v246
	s_mov_b64 exec, -1
	s_nop 1
	s_mov_b64 vcc, s[6:7]
	v_cndmask_b32_dpp v134, v4, v0, vcc row_ror:8 row_mask:0xf bank_mask:0xf
	v_cndmask_b32_dpp v135, v5, v1, vcc row_ror:8 row_mask:0xf bank_mask:0xf
	v_cndmask_b32_dpp v136, v6, v2, vcc row_ror:8 row_mask:0xf bank_mask:0xf
	v_cndmask_b32_dpp v137, v7, v3, vcc row_ror:8 row_mask:0xf bank_mask:0xf
	s_not_b64 vcc, s[6:7]
	v_cndmask_b32_dpp v130, v0, v4, vcc row_ror:8 row_mask:0xf bank_mask:0xf
	v_cndmask_b32_dpp v131, v1, v5, vcc row_ror:8 row_mask:0xf bank_mask:0xf
	v_cndmask_b32_dpp v132, v2, v6, vcc row_ror:8 row_mask:0xf bank_mask:0xf
	v_cndmask_b32_dpp v133, v3, v7, vcc row_ror:8 row_mask:0xf bank_mask:0xf
	global_store_dwordx4 v171, v[134:137], s[2:3]
	global_store_dwordx4 v171, v[130:133], s[18:19]
	s_waitcnt vmcnt(6)
	s_mov_b64 vcc, s[6:7]
	v_cndmask_b32_dpp v0, v234, v204, vcc row_ror:8 row_mask:0xf bank_mask:0xf
	v_cndmask_b32_dpp v1, v235, v205, vcc row_ror:8 row_mask:0xf bank_mask:0xf
	v_cndmask_b32_dpp v2, v236, v206, vcc row_ror:8 row_mask:0xf bank_mask:0xf
	v_cndmask_b32_dpp v3, v237, v207, vcc row_ror:8 row_mask:0xf bank_mask:0xf
	s_not_b64 vcc, s[6:7]
	v_cndmask_b32_dpp v4, v204, v234, vcc row_ror:8 row_mask:0xf bank_mask:0xf
	v_cndmask_b32_dpp v5, v205, v235, vcc row_ror:8 row_mask:0xf bank_mask:0xf
	v_cndmask_b32_dpp v6, v206, v236, vcc row_ror:8 row_mask:0xf bank_mask:0xf
	v_cndmask_b32_dpp v7, v207, v237, vcc row_ror:8 row_mask:0xf bank_mask:0xf
	s_add_u32 s14, s14, 0x28000
	s_addc_u32 s15, s15, 0
	s_add_u32 s12, s12, 0x28000
	s_addc_u32 s13, s13, 0
	global_load_dwordx4 v[204:207], v171, s[14:15] nt
	global_load_dwordx4 v[234:237], v171, s[12:13] nt
	v_lshlrev_b32_e32 v246, 16, v0
	v_and_b32_e32 v247, 0xffff0000, v0
	v_pk_fma_f32 v[118:119], v[118:119], v[142:143], v[246:247]
	v_lshlrev_b32_e32 v248, 16, v1
	v_and_b32_e32 v249, 0xffff0000, v1
	v_pk_fma_f32 v[120:121], v[120:121], v[144:145], v[248:249]
	v_lshlrev_b32_e32 v250, 16, v2
	v_and_b32_e32 v251, 0xffff0000, v2
	v_pk_fma_f32 v[114:115], v[114:115], v[150:151], v[250:251]
	v_lshlrev_b32_e32 v208, 16, v3
	v_and_b32_e32 v209, 0xffff0000, v3
	v_pk_fma_f32 v[116:117], v[116:117], v[152:153], v[208:209]
	v_lshlrev_b32_e32 v246, 16, v4
	v_and_b32_e32 v247, 0xffff0000, v4
	v_pk_fma_f32 v[110:111], v[110:111], v[138:139], v[246:247]
	v_lshlrev_b32_e32 v248, 16, v5
	v_and_b32_e32 v249, 0xffff0000, v5
	v_pk_fma_f32 v[112:113], v[112:113], v[140:141], v[248:249]
	v_lshlrev_b32_e32 v250, 16, v6
	v_and_b32_e32 v251, 0xffff0000, v6
	v_pk_fma_f32 v[106:107], v[106:107], v[146:147], v[250:251]
	v_lshlrev_b32_e32 v208, 16, v7
	v_and_b32_e32 v209, 0xffff0000, v7
	v_pk_fma_f32 v[108:109], v[108:109], v[148:149], v[208:209]
	v_cvt_pk_bf16_f32 v0, v118, v119
	v_cvt_pk_bf16_f32 v1, v120, v121
	v_cvt_pk_bf16_f32 v2, v114, v115
	v_cvt_pk_bf16_f32 v3, v116, v117
	v_cvt_pk_bf16_f32 v4, v110, v111
	v_cvt_pk_bf16_f32 v5, v112, v113
	v_cvt_pk_bf16_f32 v6, v106, v107
	v_cvt_pk_bf16_f32 v7, v108, v109
	v_mul_f32_e32 v246, v119, v119
	v_mul_f32_e32 v248, v121, v121
	v_fmac_f32_e32 v246, v118, v118
	v_fmac_f32_e32 v248, v120, v120
	v_add_f32_e32 v246, v246, v248
	v_mul_f32_e32 v248, v115, v115
	v_fmac_f32_e32 v248, v114, v114
	v_add_f32_e32 v246, v246, v248
	v_mul_f32_e32 v248, v117, v117
	v_fmac_f32_e32 v248, v116, v116
	v_add_f32_e32 v246, v248, v246
	v_mul_f32_e32 v247, v111, v111
	v_mul_f32_e32 v248, v113, v113
	v_fmac_f32_e32 v247, v110, v110
	v_fmac_f32_e32 v248, v112, v112
	v_add_f32_e32 v247, v247, v248
	v_mul_f32_e32 v248, v107, v107
	v_fmac_f32_e32 v248, v106, v106
	v_add_f32_e32 v247, v247, v248
	v_mul_f32_e32 v248, v109, v109
	v_fmac_f32_e32 v248, v108, v108
	v_add_f32_e32 v247, v248, v247
	v_add_f32_e32 v246, v246, v247
	v_mov_b32_e32 v247, v246
	s_nop 1
	v_permlane16_swap_b32_e32 v246, v247
	s_nop 1
	v_add_f32_e32 v246, v246, v247
	v_mov_b32_e32 v247, v246
	s_nop 1
	v_permlane32_swap_b32_e32 v246, v247
	v_add_u32_e32 v248, s8, v223
	s_nop 0
	v_add_f32_e32 v246, v246, v247
	s_mov_b64 exec, s[44:45]
	ds_write_b32 v248, v246 offset:256
	s_mov_b64 exec, -1
	s_add_u32 s2, s2, 0x8000
	s_addc_u32 s3, s3, 0
	s_add_u32 s18, s18, 0x8000
	s_addc_u32 s19, s19, 0
	s_mov_b64 vcc, s[6:7]
	v_cndmask_b32_dpp v118, v4, v0, vcc row_ror:8 row_mask:0xf bank_mask:0xf
	v_cndmask_b32_dpp v119, v5, v1, vcc row_ror:8 row_mask:0xf bank_mask:0xf
	v_cndmask_b32_dpp v120, v6, v2, vcc row_ror:8 row_mask:0xf bank_mask:0xf
	v_cndmask_b32_dpp v121, v7, v3, vcc row_ror:8 row_mask:0xf bank_mask:0xf
	s_not_b64 vcc, s[6:7]
	v_cndmask_b32_dpp v114, v0, v4, vcc row_ror:8 row_mask:0xf bank_mask:0xf
	v_cndmask_b32_dpp v115, v1, v5, vcc row_ror:8 row_mask:0xf bank_mask:0xf
	v_cndmask_b32_dpp v116, v2, v6, vcc row_ror:8 row_mask:0xf bank_mask:0xf
	v_cndmask_b32_dpp v117, v3, v7, vcc row_ror:8 row_mask:0xf bank_mask:0xf
	global_store_dwordx4 v171, v[118:121], s[2:3]
	global_store_dwordx4 v171, v[114:117], s[18:19]
	s_waitcnt vmcnt(8)
	s_mov_b64 vcc, s[6:7]
	v_cndmask_b32_dpp v0, v242, v238, vcc row_ror:8 row_mask:0xf bank_mask:0xf
	v_cndmask_b32_dpp v1, v243, v239, vcc row_ror:8 row_mask:0xf bank_mask:0xf
	v_cndmask_b32_dpp v2, v244, v240, vcc row_ror:8 row_mask:0xf bank_mask:0xf
	v_cndmask_b32_dpp v3, v245, v241, vcc row_ror:8 row_mask:0xf bank_mask:0xf
	s_not_b64 vcc, s[6:7]
	v_cndmask_b32_dpp v4, v238, v242, vcc row_ror:8 row_mask:0xf bank_mask:0xf
	v_cndmask_b32_dpp v5, v239, v243, vcc row_ror:8 row_mask:0xf bank_mask:0xf
	v_cndmask_b32_dpp v6, v240, v244, vcc row_ror:8 row_mask:0xf bank_mask:0xf
	v_cndmask_b32_dpp v7, v241, v245, vcc row_ror:8 row_mask:0xf bank_mask:0xf
	s_add_u32 s14, s14, 0x8000
	s_addc_u32 s15, s15, 0
	s_add_u32 s12, s12, 0x8000
	s_addc_u32 s13, s13, 0
	global_load_dwordx4 v[238:241], v171, s[14:15] nt
	global_load_dwordx4 v[242:245], v171, s[12:13] nt
	v_lshlrev_b32_e32 v246, 16, v0
	v_and_b32_e32 v247, 0xffff0000, v0
	v_pk_fma_f32 v[102:103], v[102:103], v[142:143], v[246:247]
	v_lshlrev_b32_e32 v248, 16, v1
	v_and_b32_e32 v249, 0xffff0000, v1
	v_pk_fma_f32 v[104:105], v[104:105], v[144:145], v[248:249]
	v_lshlrev_b32_e32 v250, 16, v2
	v_and_b32_e32 v251, 0xffff0000, v2
	v_pk_fma_f32 v[98:99], v[98:99], v[150:151], v[250:251]
	v_lshlrev_b32_e32 v208, 16, v3
	v_and_b32_e32 v209, 0xffff0000, v3
	v_pk_fma_f32 v[100:101], v[100:101], v[152:153], v[208:209]
	v_lshlrev_b32_e32 v246, 16, v4
	v_and_b32_e32 v247, 0xffff0000, v4
	v_pk_fma_f32 v[92:93], v[92:93], v[138:139], v[246:247]
	v_lshlrev_b32_e32 v248, 16, v5
	v_and_b32_e32 v249, 0xffff0000, v5
	v_pk_fma_f32 v[94:95], v[94:95], v[140:141], v[248:249]
	v_lshlrev_b32_e32 v250, 16, v6
	v_and_b32_e32 v251, 0xffff0000, v6
	v_pk_fma_f32 v[88:89], v[88:89], v[146:147], v[250:251]
	v_lshlrev_b32_e32 v208, 16, v7
	v_and_b32_e32 v209, 0xffff0000, v7
	v_pk_fma_f32 v[90:91], v[90:91], v[148:149], v[208:209]
	v_cvt_pk_bf16_f32 v0, v102, v103
	v_cvt_pk_bf16_f32 v1, v104, v105
	v_cvt_pk_bf16_f32 v2, v98, v99
	v_cvt_pk_bf16_f32 v3, v100, v101
	v_cvt_pk_bf16_f32 v4, v92, v93
	v_cvt_pk_bf16_f32 v5, v94, v95
	v_cvt_pk_bf16_f32 v6, v88, v89
	v_cvt_pk_bf16_f32 v7, v90, v91
	v_mul_f32_e32 v246, v103, v103
	v_mul_f32_e32 v248, v105, v105
	v_fmac_f32_e32 v246, v102, v102
	v_fmac_f32_e32 v248, v104, v104
	v_add_f32_e32 v246, v246, v248
	v_mul_f32_e32 v248, v99, v99
	v_fmac_f32_e32 v248, v98, v98
	v_add_f32_e32 v246, v246, v248
	v_mul_f32_e32 v248, v101, v101
	v_fmac_f32_e32 v248, v100, v100
	v_add_f32_e32 v246, v248, v246
	v_mul_f32_e32 v247, v93, v93
	v_mul_f32_e32 v248, v95, v95
	v_fmac_f32_e32 v247, v92, v92
	v_fmac_f32_e32 v248, v94, v94
	v_add_f32_e32 v247, v247, v248
	v_mul_f32_e32 v248, v89, v89
	v_fmac_f32_e32 v248, v88, v88
	v_add_f32_e32 v247, v247, v248
	v_mul_f32_e32 v248, v91, v91
	v_fmac_f32_e32 v248, v90, v90
	v_add_f32_e32 v247, v248, v247
	v_add_f32_e32 v246, v246, v247
	v_mov_b32_e32 v247, v246
	s_nop 1
	v_permlane16_swap_b32_e32 v246, v247
	s_nop 1
	v_add_f32_e32 v246, v246, v247
	v_mov_b32_e32 v247, v246
	s_nop 1
	v_permlane32_swap_b32_e32 v246, v247
	v_add_u32_e32 v248, s8, v223
	s_nop 0
	v_add_f32_e32 v246, v246, v247
	s_mov_b64 exec, s[44:45]
	ds_write_b32 v248, v246 offset:512
	s_mov_b64 exec, -1
	s_add_u32 s2, s2, 0x8000
	s_addc_u32 s3, s3, 0
	s_add_u32 s18, s18, 0x8000
	s_addc_u32 s19, s19, 0
	s_mov_b64 vcc, s[6:7]
	v_cndmask_b32_dpp v102, v4, v0, vcc row_ror:8 row_mask:0xf bank_mask:0xf
	v_cndmask_b32_dpp v103, v5, v1, vcc row_ror:8 row_mask:0xf bank_mask:0xf
	v_cndmask_b32_dpp v104, v6, v2, vcc row_ror:8 row_mask:0xf bank_mask:0xf
	v_cndmask_b32_dpp v105, v7, v3, vcc row_ror:8 row_mask:0xf bank_mask:0xf
	s_not_b64 vcc, s[6:7]
	v_cndmask_b32_dpp v98, v0, v4, vcc row_ror:8 row_mask:0xf bank_mask:0xf
	v_cndmask_b32_dpp v99, v1, v5, vcc row_ror:8 row_mask:0xf bank_mask:0xf
	v_cndmask_b32_dpp v100, v2, v6, vcc row_ror:8 row_mask:0xf bank_mask:0xf
	v_cndmask_b32_dpp v101, v3, v7, vcc row_ror:8 row_mask:0xf bank_mask:0xf
	global_store_dwordx4 v171, v[102:105], s[2:3]
	global_store_dwordx4 v171, v[98:101], s[18:19]
	s_waitcnt vmcnt(10)
	s_mov_b64 vcc, s[6:7]
	v_cndmask_b32_dpp v0, v200, v196, vcc row_ror:8 row_mask:0xf bank_mask:0xf
	v_cndmask_b32_dpp v1, v201, v197, vcc row_ror:8 row_mask:0xf bank_mask:0xf
	v_cndmask_b32_dpp v2, v202, v198, vcc row_ror:8 row_mask:0xf bank_mask:0xf
	v_cndmask_b32_dpp v3, v203, v199, vcc row_ror:8 row_mask:0xf bank_mask:0xf
	s_not_b64 vcc, s[6:7]
	v_cndmask_b32_dpp v4, v196, v200, vcc row_ror:8 row_mask:0xf bank_mask:0xf
	v_cndmask_b32_dpp v5, v197, v201, vcc row_ror:8 row_mask:0xf bank_mask:0xf
	v_cndmask_b32_dpp v6, v198, v202, vcc row_ror:8 row_mask:0xf bank_mask:0xf
	v_cndmask_b32_dpp v7, v199, v203, vcc row_ror:8 row_mask:0xf bank_mask:0xf
	s_add_u32 s14, s14, 0x8000
	s_addc_u32 s15, s15, 0
	s_add_u32 s12, s12, 0x8000
	s_addc_u32 s13, s13, 0
	global_load_dwordx4 v[196:199], v171, s[14:15] nt
	global_load_dwordx4 v[200:203], v171, s[12:13] nt
	v_lshlrev_b32_e32 v246, 16, v0
	v_and_b32_e32 v247, 0xffff0000, v0
	v_pk_fma_f32 v[84:85], v[84:85], v[142:143], v[246:247]
	v_lshlrev_b32_e32 v248, 16, v1
	v_and_b32_e32 v249, 0xffff0000, v1
	v_pk_fma_f32 v[86:87], v[86:87], v[144:145], v[248:249]
	v_lshlrev_b32_e32 v250, 16, v2
	v_and_b32_e32 v251, 0xffff0000, v2
	v_pk_fma_f32 v[80:81], v[80:81], v[150:151], v[250:251]
	v_lshlrev_b32_e32 v208, 16, v3
	v_and_b32_e32 v209, 0xffff0000, v3
	v_pk_fma_f32 v[82:83], v[82:83], v[152:153], v[208:209]
	v_lshlrev_b32_e32 v246, 16, v4
	v_and_b32_e32 v247, 0xffff0000, v4
	v_pk_fma_f32 v[76:77], v[76:77], v[138:139], v[246:247]
	v_lshlrev_b32_e32 v248, 16, v5
	v_and_b32_e32 v249, 0xffff0000, v5
	v_pk_fma_f32 v[78:79], v[78:79], v[140:141], v[248:249]
	v_lshlrev_b32_e32 v250, 16, v6
	v_and_b32_e32 v251, 0xffff0000, v6
	v_pk_fma_f32 v[72:73], v[72:73], v[146:147], v[250:251]
	v_lshlrev_b32_e32 v208, 16, v7
	v_and_b32_e32 v209, 0xffff0000, v7
	v_pk_fma_f32 v[74:75], v[74:75], v[148:149], v[208:209]
	v_cvt_pk_bf16_f32 v0, v84, v85
	v_cvt_pk_bf16_f32 v1, v86, v87
	v_cvt_pk_bf16_f32 v2, v80, v81
	v_cvt_pk_bf16_f32 v3, v82, v83
	v_cvt_pk_bf16_f32 v4, v76, v77
	v_cvt_pk_bf16_f32 v5, v78, v79
	v_cvt_pk_bf16_f32 v6, v72, v73
	v_cvt_pk_bf16_f32 v7, v74, v75
	v_mul_f32_e32 v246, v85, v85
	v_mul_f32_e32 v248, v87, v87
	v_fmac_f32_e32 v246, v84, v84
	v_fmac_f32_e32 v248, v86, v86
	v_add_f32_e32 v246, v246, v248
	v_mul_f32_e32 v248, v81, v81
	v_fmac_f32_e32 v248, v80, v80
	v_add_f32_e32 v246, v246, v248
	v_mul_f32_e32 v248, v83, v83
	v_fmac_f32_e32 v248, v82, v82
	v_add_f32_e32 v246, v248, v246
	v_mul_f32_e32 v247, v77, v77
	v_mul_f32_e32 v248, v79, v79
	v_fmac_f32_e32 v247, v76, v76
	v_fmac_f32_e32 v248, v78, v78
	v_add_f32_e32 v247, v247, v248
	v_mul_f32_e32 v248, v73, v73
	v_fmac_f32_e32 v248, v72, v72
	v_add_f32_e32 v247, v247, v248
	v_mul_f32_e32 v248, v75, v75
	v_fmac_f32_e32 v248, v74, v74
	v_add_f32_e32 v247, v248, v247
	v_add_f32_e32 v246, v246, v247
	v_mov_b32_e32 v247, v246
	s_nop 1
	v_permlane16_swap_b32_e32 v246, v247
	s_nop 1
	v_add_f32_e32 v246, v246, v247
	v_mov_b32_e32 v247, v246
	s_nop 1
	v_permlane32_swap_b32_e32 v246, v247
	v_add_u32_e32 v248, s8, v223
	s_nop 0
	v_add_f32_e32 v246, v246, v247
	s_mov_b64 exec, s[44:45]
	ds_write_b32 v248, v246 offset:768
	s_mov_b64 exec, -1
	s_add_u32 s2, s2, 0x8000
	s_addc_u32 s3, s3, 0
	s_add_u32 s18, s18, 0x8000
	s_addc_u32 s19, s19, 0
	s_mov_b64 vcc, s[6:7]
	v_cndmask_b32_dpp v84, v4, v0, vcc row_ror:8 row_mask:0xf bank_mask:0xf
	v_cndmask_b32_dpp v85, v5, v1, vcc row_ror:8 row_mask:0xf bank_mask:0xf
	v_cndmask_b32_dpp v86, v6, v2, vcc row_ror:8 row_mask:0xf bank_mask:0xf
	v_cndmask_b32_dpp v87, v7, v3, vcc row_ror:8 row_mask:0xf bank_mask:0xf
	s_not_b64 vcc, s[6:7]
	v_cndmask_b32_dpp v80, v0, v4, vcc row_ror:8 row_mask:0xf bank_mask:0xf
	v_cndmask_b32_dpp v81, v1, v5, vcc row_ror:8 row_mask:0xf bank_mask:0xf
	v_cndmask_b32_dpp v82, v2, v6, vcc row_ror:8 row_mask:0xf bank_mask:0xf
	v_cndmask_b32_dpp v83, v3, v7, vcc row_ror:8 row_mask:0xf bank_mask:0xf
	global_store_dwordx4 v171, v[84:87], s[2:3]
	global_store_dwordx4 v171, v[80:83], s[18:19]
	s_waitcnt vmcnt(10)
	s_mov_b64 vcc, s[6:7]
	v_cndmask_b32_dpp v0, v234, v204, vcc row_ror:8 row_mask:0xf bank_mask:0xf
	v_cndmask_b32_dpp v1, v235, v205, vcc row_ror:8 row_mask:0xf bank_mask:0xf
	v_cndmask_b32_dpp v2, v236, v206, vcc row_ror:8 row_mask:0xf bank_mask:0xf
	v_cndmask_b32_dpp v3, v237, v207, vcc row_ror:8 row_mask:0xf bank_mask:0xf
	s_not_b64 vcc, s[6:7]
	v_cndmask_b32_dpp v4, v204, v234, vcc row_ror:8 row_mask:0xf bank_mask:0xf
	v_cndmask_b32_dpp v5, v205, v235, vcc row_ror:8 row_mask:0xf bank_mask:0xf
	v_cndmask_b32_dpp v6, v206, v236, vcc row_ror:8 row_mask:0xf bank_mask:0xf
	v_cndmask_b32_dpp v7, v207, v237, vcc row_ror:8 row_mask:0xf bank_mask:0xf
	s_add_u32 s14, s14, 0x8000
	s_addc_u32 s15, s15, 0
	s_add_u32 s12, s12, 0x8000
	s_addc_u32 s13, s13, 0
	global_load_dwordx4 v[204:207], v171, s[14:15] nt
	global_load_dwordx4 v[234:237], v171, s[12:13] nt
	v_lshlrev_b32_e32 v246, 16, v0
	v_and_b32_e32 v247, 0xffff0000, v0
	v_pk_fma_f32 v[68:69], v[68:69], v[142:143], v[246:247]
	v_lshlrev_b32_e32 v248, 16, v1
	v_and_b32_e32 v249, 0xffff0000, v1
	v_pk_fma_f32 v[70:71], v[70:71], v[144:145], v[248:249]
	v_lshlrev_b32_e32 v250, 16, v2
	v_and_b32_e32 v251, 0xffff0000, v2
	v_pk_fma_f32 v[64:65], v[64:65], v[150:151], v[250:251]
	v_lshlrev_b32_e32 v208, 16, v3
	v_and_b32_e32 v209, 0xffff0000, v3
	v_pk_fma_f32 v[66:67], v[66:67], v[152:153], v[208:209]
	v_lshlrev_b32_e32 v246, 16, v4
	v_and_b32_e32 v247, 0xffff0000, v4
	v_pk_fma_f32 v[60:61], v[60:61], v[138:139], v[246:247]
	v_lshlrev_b32_e32 v248, 16, v5
	v_and_b32_e32 v249, 0xffff0000, v5
	v_pk_fma_f32 v[62:63], v[62:63], v[140:141], v[248:249]
	v_lshlrev_b32_e32 v250, 16, v6
	v_and_b32_e32 v251, 0xffff0000, v6
	v_pk_fma_f32 v[56:57], v[56:57], v[146:147], v[250:251]
	v_lshlrev_b32_e32 v208, 16, v7
	v_and_b32_e32 v209, 0xffff0000, v7
	v_pk_fma_f32 v[58:59], v[58:59], v[148:149], v[208:209]
	v_cvt_pk_bf16_f32 v0, v68, v69
	v_cvt_pk_bf16_f32 v1, v70, v71
	v_cvt_pk_bf16_f32 v2, v64, v65
	v_cvt_pk_bf16_f32 v3, v66, v67
	v_cvt_pk_bf16_f32 v4, v60, v61
	v_cvt_pk_bf16_f32 v5, v62, v63
	v_cvt_pk_bf16_f32 v6, v56, v57
	v_cvt_pk_bf16_f32 v7, v58, v59
	v_mul_f32_e32 v246, v69, v69
	v_mul_f32_e32 v248, v71, v71
	v_fmac_f32_e32 v246, v68, v68
	v_fmac_f32_e32 v248, v70, v70
	v_add_f32_e32 v246, v246, v248
	v_mul_f32_e32 v248, v65, v65
	v_fmac_f32_e32 v248, v64, v64
	v_add_f32_e32 v246, v246, v248
	v_mul_f32_e32 v248, v67, v67
	v_fmac_f32_e32 v248, v66, v66
	v_add_f32_e32 v246, v248, v246
	v_mul_f32_e32 v247, v61, v61
	v_mul_f32_e32 v248, v63, v63
	v_fmac_f32_e32 v247, v60, v60
	v_fmac_f32_e32 v248, v62, v62
	v_add_f32_e32 v247, v247, v248
	v_mul_f32_e32 v248, v57, v57
	v_fmac_f32_e32 v248, v56, v56
	v_add_f32_e32 v247, v247, v248
	v_mul_f32_e32 v248, v59, v59
	v_fmac_f32_e32 v248, v58, v58
	v_add_f32_e32 v247, v248, v247
	v_add_f32_e32 v246, v246, v247
	v_mov_b32_e32 v247, v246
	s_nop 1
	v_permlane16_swap_b32_e32 v246, v247
	s_nop 1
	v_add_f32_e32 v246, v246, v247
	v_mov_b32_e32 v247, v246
	s_nop 1
	v_permlane32_swap_b32_e32 v246, v247
	v_add_u32_e32 v248, s8, v223
	s_nop 0
	v_add_f32_e32 v246, v246, v247
	s_mov_b64 exec, s[44:45]
	ds_write_b32 v248, v246 offset:2048
	s_mov_b64 exec, -1
	s_add_u32 s2, s2, 0x28000
	s_addc_u32 s3, s3, 0
	s_add_u32 s18, s18, 0x28000
	s_addc_u32 s19, s19, 0
	s_mov_b64 vcc, s[6:7]
	v_cndmask_b32_dpp v68, v4, v0, vcc row_ror:8 row_mask:0xf bank_mask:0xf
	v_cndmask_b32_dpp v69, v5, v1, vcc row_ror:8 row_mask:0xf bank_mask:0xf
	v_cndmask_b32_dpp v70, v6, v2, vcc row_ror:8 row_mask:0xf bank_mask:0xf
	v_cndmask_b32_dpp v71, v7, v3, vcc row_ror:8 row_mask:0xf bank_mask:0xf
	s_not_b64 vcc, s[6:7]
	v_cndmask_b32_dpp v64, v0, v4, vcc row_ror:8 row_mask:0xf bank_mask:0xf
	v_cndmask_b32_dpp v65, v1, v5, vcc row_ror:8 row_mask:0xf bank_mask:0xf
	v_cndmask_b32_dpp v66, v2, v6, vcc row_ror:8 row_mask:0xf bank_mask:0xf
	v_cndmask_b32_dpp v67, v3, v7, vcc row_ror:8 row_mask:0xf bank_mask:0xf
	global_store_dwordx4 v171, v[68:71], s[2:3]
	global_store_dwordx4 v171, v[64:67], s[18:19]
	s_waitcnt vmcnt(10)
	s_mov_b64 vcc, s[6:7]
	v_cndmask_b32_dpp v0, v242, v238, vcc row_ror:8 row_mask:0xf bank_mask:0xf
	v_cndmask_b32_dpp v1, v243, v239, vcc row_ror:8 row_mask:0xf bank_mask:0xf
	v_cndmask_b32_dpp v2, v244, v240, vcc row_ror:8 row_mask:0xf bank_mask:0xf
	v_cndmask_b32_dpp v3, v245, v241, vcc row_ror:8 row_mask:0xf bank_mask:0xf
	s_not_b64 vcc, s[6:7]
	v_cndmask_b32_dpp v4, v238, v242, vcc row_ror:8 row_mask:0xf bank_mask:0xf
	v_cndmask_b32_dpp v5, v239, v243, vcc row_ror:8 row_mask:0xf bank_mask:0xf
	v_cndmask_b32_dpp v6, v240, v244, vcc row_ror:8 row_mask:0xf bank_mask:0xf
	v_cndmask_b32_dpp v7, v241, v245, vcc row_ror:8 row_mask:0xf bank_mask:0xf
	v_lshlrev_b32_e32 v246, 16, v0
	v_and_b32_e32 v247, 0xffff0000, v0
	v_pk_fma_f32 v[52:53], v[52:53], v[142:143], v[246:247]
	v_lshlrev_b32_e32 v248, 16, v1
	v_and_b32_e32 v249, 0xffff0000, v1
	v_pk_fma_f32 v[54:55], v[54:55], v[144:145], v[248:249]
	v_lshlrev_b32_e32 v250, 16, v2
	v_and_b32_e32 v251, 0xffff0000, v2
	v_pk_fma_f32 v[48:49], v[48:49], v[150:151], v[250:251]
	v_lshlrev_b32_e32 v208, 16, v3
	v_and_b32_e32 v209, 0xffff0000, v3
	v_pk_fma_f32 v[50:51], v[50:51], v[152:153], v[208:209]
	v_lshlrev_b32_e32 v246, 16, v4
	v_and_b32_e32 v247, 0xffff0000, v4
	v_pk_fma_f32 v[44:45], v[44:45], v[138:139], v[246:247]
	v_lshlrev_b32_e32 v248, 16, v5
	v_and_b32_e32 v249, 0xffff0000, v5
	v_pk_fma_f32 v[46:47], v[46:47], v[140:141], v[248:249]
	v_lshlrev_b32_e32 v250, 16, v6
	v_and_b32_e32 v251, 0xffff0000, v6
	v_pk_fma_f32 v[40:41], v[40:41], v[146:147], v[250:251]
	v_lshlrev_b32_e32 v208, 16, v7
	v_and_b32_e32 v209, 0xffff0000, v7
	v_pk_fma_f32 v[42:43], v[42:43], v[148:149], v[208:209]
	v_cvt_pk_bf16_f32 v0, v52, v53
	v_cvt_pk_bf16_f32 v1, v54, v55
	v_cvt_pk_bf16_f32 v2, v48, v49
	v_cvt_pk_bf16_f32 v3, v50, v51
	v_cvt_pk_bf16_f32 v4, v44, v45
	v_cvt_pk_bf16_f32 v5, v46, v47
	v_cvt_pk_bf16_f32 v6, v40, v41
	v_cvt_pk_bf16_f32 v7, v42, v43
	v_mul_f32_e32 v246, v53, v53
	v_mul_f32_e32 v248, v55, v55
	v_fmac_f32_e32 v246, v52, v52
	v_fmac_f32_e32 v248, v54, v54
	v_add_f32_e32 v246, v246, v248
	v_mul_f32_e32 v248, v49, v49
	v_fmac_f32_e32 v248, v48, v48
	v_add_f32_e32 v246, v246, v248
	v_mul_f32_e32 v248, v51, v51
	v_fmac_f32_e32 v248, v50, v50
	v_add_f32_e32 v246, v248, v246
	v_mul_f32_e32 v247, v45, v45
	v_mul_f32_e32 v248, v47, v47
	v_fmac_f32_e32 v247, v44, v44
	v_fmac_f32_e32 v248, v46, v46
	v_add_f32_e32 v247, v247, v248
	v_mul_f32_e32 v248, v41, v41
	v_fmac_f32_e32 v248, v40, v40
	v_add_f32_e32 v247, v247, v248
	v_mul_f32_e32 v248, v43, v43
	v_fmac_f32_e32 v248, v42, v42
	v_add_f32_e32 v247, v248, v247
	v_add_f32_e32 v246, v246, v247
	v_mov_b32_e32 v247, v246
	s_nop 1
	v_permlane16_swap_b32_e32 v246, v247
	s_nop 1
	v_add_f32_e32 v246, v246, v247
	v_mov_b32_e32 v247, v246
	s_nop 1
	v_permlane32_swap_b32_e32 v246, v247
	v_add_u32_e32 v248, s8, v223
	s_nop 0
	v_add_f32_e32 v246, v246, v247
	s_mov_b64 exec, s[44:45]
	ds_write_b32 v248, v246 offset:2304
	s_mov_b64 exec, -1
	s_add_u32 s2, s2, 0x8000
	s_addc_u32 s3, s3, 0
	s_add_u32 s18, s18, 0x8000
	s_addc_u32 s19, s19, 0
	s_mov_b64 vcc, s[6:7]
	v_cndmask_b32_dpp v52, v4, v0, vcc row_ror:8 row_mask:0xf bank_mask:0xf
	v_cndmask_b32_dpp v53, v5, v1, vcc row_ror:8 row_mask:0xf bank_mask:0xf
	v_cndmask_b32_dpp v54, v6, v2, vcc row_ror:8 row_mask:0xf bank_mask:0xf
	v_cndmask_b32_dpp v55, v7, v3, vcc row_ror:8 row_mask:0xf bank_mask:0xf
	s_not_b64 vcc, s[6:7]
	v_cndmask_b32_dpp v48, v0, v4, vcc row_ror:8 row_mask:0xf bank_mask:0xf
	v_cndmask_b32_dpp v49, v1, v5, vcc row_ror:8 row_mask:0xf bank_mask:0xf
	v_cndmask_b32_dpp v50, v2, v6, vcc row_ror:8 row_mask:0xf bank_mask:0xf
	v_cndmask_b32_dpp v51, v3, v7, vcc row_ror:8 row_mask:0xf bank_mask:0xf
	global_store_dwordx4 v171, v[52:55], s[2:3]
	global_store_dwordx4 v171, v[48:51], s[18:19]
	s_waitcnt vmcnt(8)
	s_mov_b64 vcc, s[6:7]
	v_cndmask_b32_dpp v0, v200, v196, vcc row_ror:8 row_mask:0xf bank_mask:0xf
	v_cndmask_b32_dpp v1, v201, v197, vcc row_ror:8 row_mask:0xf bank_mask:0xf
	v_cndmask_b32_dpp v2, v202, v198, vcc row_ror:8 row_mask:0xf bank_mask:0xf
	v_cndmask_b32_dpp v3, v203, v199, vcc row_ror:8 row_mask:0xf bank_mask:0xf
	s_not_b64 vcc, s[6:7]
	v_cndmask_b32_dpp v4, v196, v200, vcc row_ror:8 row_mask:0xf bank_mask:0xf
	v_cndmask_b32_dpp v5, v197, v201, vcc row_ror:8 row_mask:0xf bank_mask:0xf
	v_cndmask_b32_dpp v6, v198, v202, vcc row_ror:8 row_mask:0xf bank_mask:0xf
	v_cndmask_b32_dpp v7, v199, v203, vcc row_ror:8 row_mask:0xf bank_mask:0xf
	v_lshlrev_b32_e32 v246, 16, v0
	v_and_b32_e32 v247, 0xffff0000, v0
	v_pk_fma_f32 v[36:37], v[36:37], v[142:143], v[246:247]
	v_lshlrev_b32_e32 v248, 16, v1
	v_and_b32_e32 v249, 0xffff0000, v1
	v_pk_fma_f32 v[38:39], v[38:39], v[144:145], v[248:249]
	v_lshlrev_b32_e32 v250, 16, v2
	v_and_b32_e32 v251, 0xffff0000, v2
	v_pk_fma_f32 v[32:33], v[32:33], v[150:151], v[250:251]
	v_lshlrev_b32_e32 v208, 16, v3
	v_and_b32_e32 v209, 0xffff0000, v3
	v_pk_fma_f32 v[34:35], v[34:35], v[152:153], v[208:209]
	v_lshlrev_b32_e32 v246, 16, v4
	v_and_b32_e32 v247, 0xffff0000, v4
	v_pk_fma_f32 v[28:29], v[28:29], v[138:139], v[246:247]
	v_lshlrev_b32_e32 v248, 16, v5
	v_and_b32_e32 v249, 0xffff0000, v5
	v_pk_fma_f32 v[30:31], v[30:31], v[140:141], v[248:249]
	v_lshlrev_b32_e32 v250, 16, v6
	v_and_b32_e32 v251, 0xffff0000, v6
	v_pk_fma_f32 v[24:25], v[24:25], v[146:147], v[250:251]
	v_lshlrev_b32_e32 v208, 16, v7
	v_and_b32_e32 v209, 0xffff0000, v7
	v_pk_fma_f32 v[26:27], v[26:27], v[148:149], v[208:209]
	v_cvt_pk_bf16_f32 v0, v36, v37
	v_cvt_pk_bf16_f32 v1, v38, v39
	v_cvt_pk_bf16_f32 v2, v32, v33
	v_cvt_pk_bf16_f32 v3, v34, v35
	v_cvt_pk_bf16_f32 v4, v28, v29
	v_cvt_pk_bf16_f32 v5, v30, v31
	v_cvt_pk_bf16_f32 v6, v24, v25
	v_cvt_pk_bf16_f32 v7, v26, v27
	v_mul_f32_e32 v246, v37, v37
	v_mul_f32_e32 v248, v39, v39
	v_fmac_f32_e32 v246, v36, v36
	v_fmac_f32_e32 v248, v38, v38
	v_add_f32_e32 v246, v246, v248
	v_mul_f32_e32 v248, v33, v33
	v_fmac_f32_e32 v248, v32, v32
	v_add_f32_e32 v246, v246, v248
	v_mul_f32_e32 v248, v35, v35
	v_fmac_f32_e32 v248, v34, v34
	v_add_f32_e32 v246, v248, v246
	v_mul_f32_e32 v247, v29, v29
	v_mul_f32_e32 v248, v31, v31
	v_fmac_f32_e32 v247, v28, v28
	v_fmac_f32_e32 v248, v30, v30
	v_add_f32_e32 v247, v247, v248
	v_mul_f32_e32 v248, v25, v25
	v_fmac_f32_e32 v248, v24, v24
	v_add_f32_e32 v247, v247, v248
	v_mul_f32_e32 v248, v27, v27
	v_fmac_f32_e32 v248, v26, v26
	v_add_f32_e32 v247, v248, v247
	v_add_f32_e32 v246, v246, v247
	v_mov_b32_e32 v247, v246
	s_nop 1
	v_permlane16_swap_b32_e32 v246, v247
	s_nop 1
	v_add_f32_e32 v246, v246, v247
	v_mov_b32_e32 v247, v246
	s_nop 1
	v_permlane32_swap_b32_e32 v246, v247
	v_add_u32_e32 v248, s8, v223
	s_nop 0
	v_add_f32_e32 v246, v246, v247
	s_mov_b64 exec, s[44:45]
	ds_write_b32 v248, v246 offset:2560
	s_mov_b64 exec, -1
	s_add_u32 s2, s2, 0x8000
	s_addc_u32 s3, s3, 0
	s_add_u32 s18, s18, 0x8000
	s_addc_u32 s19, s19, 0
	s_mov_b64 vcc, s[6:7]
	v_cndmask_b32_dpp v36, v4, v0, vcc row_ror:8 row_mask:0xf bank_mask:0xf
	v_cndmask_b32_dpp v37, v5, v1, vcc row_ror:8 row_mask:0xf bank_mask:0xf
	v_cndmask_b32_dpp v38, v6, v2, vcc row_ror:8 row_mask:0xf bank_mask:0xf
	v_cndmask_b32_dpp v39, v7, v3, vcc row_ror:8 row_mask:0xf bank_mask:0xf
	s_not_b64 vcc, s[6:7]
	v_cndmask_b32_dpp v32, v0, v4, vcc row_ror:8 row_mask:0xf bank_mask:0xf
	v_cndmask_b32_dpp v33, v1, v5, vcc row_ror:8 row_mask:0xf bank_mask:0xf
	v_cndmask_b32_dpp v34, v2, v6, vcc row_ror:8 row_mask:0xf bank_mask:0xf
	v_cndmask_b32_dpp v35, v3, v7, vcc row_ror:8 row_mask:0xf bank_mask:0xf
	global_store_dwordx4 v171, v[36:39], s[2:3]
	global_store_dwordx4 v171, v[32:35], s[18:19]
	s_waitcnt vmcnt(6)
	s_mov_b64 vcc, s[6:7]
	v_cndmask_b32_dpp v0, v234, v204, vcc row_ror:8 row_mask:0xf bank_mask:0xf
	v_cndmask_b32_dpp v1, v235, v205, vcc row_ror:8 row_mask:0xf bank_mask:0xf
	v_cndmask_b32_dpp v2, v236, v206, vcc row_ror:8 row_mask:0xf bank_mask:0xf
	v_cndmask_b32_dpp v3, v237, v207, vcc row_ror:8 row_mask:0xf bank_mask:0xf
	s_not_b64 vcc, s[6:7]
	v_cndmask_b32_dpp v4, v204, v234, vcc row_ror:8 row_mask:0xf bank_mask:0xf
	v_cndmask_b32_dpp v5, v205, v235, vcc row_ror:8 row_mask:0xf bank_mask:0xf
	v_cndmask_b32_dpp v6, v206, v236, vcc row_ror:8 row_mask:0xf bank_mask:0xf
	v_cndmask_b32_dpp v7, v207, v237, vcc row_ror:8 row_mask:0xf bank_mask:0xf
	v_lshlrev_b32_e32 v246, 16, v0
	v_and_b32_e32 v247, 0xffff0000, v0
	v_pk_fma_f32 v[20:21], v[20:21], v[142:143], v[246:247]
	v_lshlrev_b32_e32 v248, 16, v1
	v_and_b32_e32 v249, 0xffff0000, v1
	v_pk_fma_f32 v[22:23], v[22:23], v[144:145], v[248:249]
	v_lshlrev_b32_e32 v250, 16, v2
	v_and_b32_e32 v251, 0xffff0000, v2
	v_pk_fma_f32 v[16:17], v[16:17], v[150:151], v[250:251]
	v_lshlrev_b32_e32 v208, 16, v3
	v_and_b32_e32 v209, 0xffff0000, v3
	v_pk_fma_f32 v[18:19], v[18:19], v[152:153], v[208:209]
	v_lshlrev_b32_e32 v246, 16, v4
	v_and_b32_e32 v247, 0xffff0000, v4
	v_pk_fma_f32 v[12:13], v[12:13], v[138:139], v[246:247]
	v_lshlrev_b32_e32 v248, 16, v5
	v_and_b32_e32 v249, 0xffff0000, v5
	v_pk_fma_f32 v[14:15], v[14:15], v[140:141], v[248:249]
	v_lshlrev_b32_e32 v250, 16, v6
	v_and_b32_e32 v251, 0xffff0000, v6
	v_pk_fma_f32 v[8:9], v[8:9], v[146:147], v[250:251]
	v_lshlrev_b32_e32 v208, 16, v7
	v_and_b32_e32 v209, 0xffff0000, v7
	v_pk_fma_f32 v[10:11], v[10:11], v[148:149], v[208:209]
	v_cvt_pk_bf16_f32 v0, v20, v21
	v_cvt_pk_bf16_f32 v1, v22, v23
	v_cvt_pk_bf16_f32 v2, v16, v17
	v_cvt_pk_bf16_f32 v3, v18, v19
	v_cvt_pk_bf16_f32 v4, v12, v13
	v_cvt_pk_bf16_f32 v5, v14, v15
	v_cvt_pk_bf16_f32 v6, v8, v9
	v_cvt_pk_bf16_f32 v7, v10, v11
	v_mul_f32_e32 v246, v21, v21
	v_mul_f32_e32 v248, v23, v23
	v_fmac_f32_e32 v246, v20, v20
	v_fmac_f32_e32 v248, v22, v22
	v_add_f32_e32 v246, v246, v248
	v_mul_f32_e32 v248, v17, v17
	v_fmac_f32_e32 v248, v16, v16
	v_add_f32_e32 v246, v246, v248
	v_mul_f32_e32 v248, v19, v19
	v_fmac_f32_e32 v248, v18, v18
	v_add_f32_e32 v246, v248, v246
	v_mul_f32_e32 v247, v13, v13
	v_mul_f32_e32 v248, v15, v15
	v_fmac_f32_e32 v247, v12, v12
	v_fmac_f32_e32 v248, v14, v14
	v_add_f32_e32 v247, v247, v248
	v_mul_f32_e32 v248, v9, v9
	v_fmac_f32_e32 v248, v8, v8
	v_add_f32_e32 v247, v247, v248
	v_mul_f32_e32 v248, v11, v11
	v_fmac_f32_e32 v248, v10, v10
	v_add_f32_e32 v247, v248, v247
	v_add_f32_e32 v246, v246, v247
	v_mov_b32_e32 v247, v246
	s_nop 1
	v_permlane16_swap_b32_e32 v246, v247
	s_nop 1
	v_add_f32_e32 v246, v246, v247
	v_mov_b32_e32 v247, v246
	s_nop 1
	v_permlane32_swap_b32_e32 v246, v247
	v_add_u32_e32 v248, s8, v223
	s_nop 0
	v_add_f32_e32 v246, v246, v247
	s_mov_b64 exec, s[44:45]
	ds_write_b32 v248, v246 offset:2816
	s_mov_b64 exec, -1
	s_add_u32 s2, s2, 0x8000
	s_addc_u32 s3, s3, 0
	s_add_u32 s18, s18, 0x8000
	s_addc_u32 s19, s19, 0
	s_mov_b64 vcc, s[6:7]
	v_cndmask_b32_dpp v20, v4, v0, vcc row_ror:8 row_mask:0xf bank_mask:0xf
	v_cndmask_b32_dpp v21, v5, v1, vcc row_ror:8 row_mask:0xf bank_mask:0xf
	v_cndmask_b32_dpp v22, v6, v2, vcc row_ror:8 row_mask:0xf bank_mask:0xf
	v_cndmask_b32_dpp v23, v7, v3, vcc row_ror:8 row_mask:0xf bank_mask:0xf
	s_not_b64 vcc, s[6:7]
	v_cndmask_b32_dpp v16, v0, v4, vcc row_ror:8 row_mask:0xf bank_mask:0xf
	v_cndmask_b32_dpp v17, v1, v5, vcc row_ror:8 row_mask:0xf bank_mask:0xf
	v_cndmask_b32_dpp v18, v2, v6, vcc row_ror:8 row_mask:0xf bank_mask:0xf
	v_cndmask_b32_dpp v19, v3, v7, vcc row_ror:8 row_mask:0xf bank_mask:0xf
	global_store_dwordx4 v171, v[20:23], s[2:3]
	global_store_dwordx4 v171, v[16:19], s[18:19]
	s_mov_b32 s100, 1
	s_branch .LBB0_714
